# hoist all residual-stream loads of the out-proj and MLP-down GEMM epilogues to the epilogue head (8 sites)
# baseline (speedup 1.0000x reference)
.LBB0_609:
	v_lshl_add_u32 v142, s26, 8, v144
	v_ashrrev_i32_e32 v143, 31, v142
	v_lshl_or_b32 v140, s8, 8, v146
	v_lshlrev_b64 v[150:151], 11, v[142:143]
	v_ashrrev_i32_e32 v141, 31, v140
	v_lshl_add_u64 v[150:151], s[2:3], 0, v[150:151]
	v_lshl_add_u64 v[150:151], v[140:141], 1, v[150:151]
	s_mov_b64 s[98:99], 0x8000
	s_mov_b64 s[100:101], 0x28000
	global_load_dwordx2 v[156:157], v[150:151], off
	global_load_dwordx2 v[158:159], v[150:151], off offset:32
	global_load_dwordx2 v[160:161], v[150:151], off offset:256
	global_load_dwordx2 v[162:163], v[150:151], off offset:288
	v_lshl_add_u64 v[222:223], v[150:151], 0, s[98:99]
	global_load_dwordx2 v[164:165], v[222:223], off
	global_load_dwordx2 v[166:167], v[222:223], off offset:32
	global_load_dwordx2 v[168:169], v[222:223], off offset:256
	global_load_dwordx2 v[170:171], v[222:223], off offset:288
	v_lshl_add_u64 v[222:223], v[222:223], 0, s[98:99]
	global_load_dwordx2 v[172:173], v[222:223], off
	global_load_dwordx2 v[174:175], v[222:223], off offset:32
	global_load_dwordx2 v[176:177], v[222:223], off offset:256
	global_load_dwordx2 v[178:179], v[222:223], off offset:288
	v_lshl_add_u64 v[222:223], v[222:223], 0, s[98:99]
	global_load_dwordx2 v[180:181], v[222:223], off
	global_load_dwordx2 v[182:183], v[222:223], off offset:32
	global_load_dwordx2 v[184:185], v[222:223], off offset:256
	global_load_dwordx2 v[186:187], v[222:223], off offset:288
	v_lshl_add_u64 v[222:223], v[222:223], 0, s[100:101]
	global_load_dwordx2 v[188:189], v[222:223], off
	global_load_dwordx2 v[190:191], v[222:223], off offset:32
	global_load_dwordx2 v[192:193], v[222:223], off offset:256
	global_load_dwordx2 v[194:195], v[222:223], off offset:288
	v_lshl_add_u64 v[222:223], v[222:223], 0, s[98:99]
	global_load_dwordx2 v[196:197], v[222:223], off
	global_load_dwordx2 v[198:199], v[222:223], off offset:32
	global_load_dwordx2 v[200:201], v[222:223], off offset:256
	global_load_dwordx2 v[202:203], v[222:223], off offset:288
	v_lshl_add_u64 v[222:223], v[222:223], 0, s[98:99]
	global_load_dwordx2 v[204:205], v[222:223], off
	global_load_dwordx2 v[208:209], v[222:223], off offset:32
	global_load_dwordx2 v[210:211], v[222:223], off offset:256
	global_load_dwordx2 v[212:213], v[222:223], off offset:288
	v_lshl_add_u64 v[222:223], v[222:223], 0, s[98:99]
	global_load_dwordx2 v[214:215], v[222:223], off
	global_load_dwordx2 v[216:217], v[222:223], off offset:32
	global_load_dwordx2 v[218:219], v[222:223], off offset:256
	global_load_dwordx2 v[220:221], v[222:223], off offset:288
	s_lshl_b32 s26, s8, 2
	s_ashr_i32 s27, s26, 31
	s_waitcnt vmcnt(31)
	v_lshlrev_b32_e32 v154, 16, v156
	v_and_b32_e32 v155, 0xffff0000, v156
	v_lshlrev_b32_e32 v152, 16, v157
	v_and_b32_e32 v153, 0xffff0000, v157
	v_pk_add_f32 v[126:127], v[126:127], v[152:153]
	v_pk_add_f32 v[124:125], v[124:125], v[154:155]
	s_nop 0
	v_cvt_pk_bf16_f32 v152, v124, v125
	v_cvt_pk_bf16_f32 v153, v126, v127
	v_mul_f32_e32 v125, v125, v125
	global_store_dwordx2 v[150:151], v[152:153], off
	v_mul_f32_e32 v127, v127, v127
	v_fmac_f32_e32 v125, v124, v124
	v_fmac_f32_e32 v127, v126, v126
	v_add_f32_e32 v124, v125, v127
	s_waitcnt vmcnt(31)
	v_lshlrev_b32_e32 v152, 16, v158
	v_and_b32_e32 v153, 0xffff0000, v158
	v_lshlrev_b32_e32 v154, 16, v159
	v_and_b32_e32 v155, 0xffff0000, v159
	v_pk_add_f32 v[122:123], v[122:123], v[154:155]
	v_pk_add_f32 v[120:121], v[120:121], v[152:153]
	s_nop 0
	v_cvt_pk_bf16_f32 v152, v120, v121
	v_cvt_pk_bf16_f32 v153, v122, v123
	v_mul_f32_e32 v121, v121, v121
	global_store_dwordx2 v[150:151], v[152:153], off offset:32
	v_mul_f32_e32 v123, v123, v123
	v_fmac_f32_e32 v121, v120, v120
	v_fmac_f32_e32 v123, v122, v122
	v_add_f32_e32 v120, v121, v123
	v_add_f32_e32 v120, v124, v120
	s_waitcnt vmcnt(31)
	v_lshlrev_b32_e32 v152, 16, v160
	v_and_b32_e32 v153, 0xffff0000, v160
	v_lshlrev_b32_e32 v154, 16, v161
	v_and_b32_e32 v155, 0xffff0000, v161
	v_pk_add_f32 v[118:119], v[118:119], v[154:155]
	v_pk_add_f32 v[116:117], v[116:117], v[152:153]
	s_nop 0
	v_cvt_pk_bf16_f32 v152, v116, v117
	v_cvt_pk_bf16_f32 v153, v118, v119
	v_mul_f32_e32 v117, v117, v117
	v_mul_f32_e32 v119, v119, v119
	v_fmac_f32_e32 v117, v116, v116
	v_fmac_f32_e32 v119, v118, v118
	v_add_f32_e32 v116, v117, v119
	v_add_f32_e32 v120, v120, v116
	global_store_dwordx2 v[150:151], v[152:153], off offset:256
	s_waitcnt vmcnt(31)
	v_lshlrev_b32_e32 v116, 16, v162
	v_and_b32_e32 v117, 0xffff0000, v162
	v_lshlrev_b32_e32 v118, 16, v163
	v_and_b32_e32 v119, 0xffff0000, v163
	v_pk_add_f32 v[114:115], v[114:115], v[118:119]
	v_pk_add_f32 v[112:113], v[112:113], v[116:117]
	v_mul_f32_e32 v117, v115, v115
	v_mul_f32_e32 v116, v113, v113
	v_fmac_f32_e32 v116, v112, v112
	v_fmac_f32_e32 v117, v114, v114
	v_add_f32_e32 v116, v116, v117
	v_add_f32_e32 v116, v120, v116
	ds_swizzle_b32 v117, v116 offset:swizzle(SWAP,16)
	v_cvt_pk_bf16_f32 v112, v112, v113
	v_cvt_pk_bf16_f32 v113, v114, v115
	global_store_dwordx2 v[150:151], v[112:113], off offset:288
	s_waitcnt lgkmcnt(0)
	v_add_f32_e32 v112, v116, v117
	v_mov_b32_e32 v113, v112
	s_nop 1
	v_permlane32_swap_b32_e32 v112, v113
	s_and_saveexec_b64 s[28:29], s[4:5]
	s_cbranch_execz .LBB0_611
	v_add_f32_e32 v114, v112, v113
	v_lshlrev_b64 v[112:113], 6, v[142:143]
	v_lshl_add_u64 v[112:113], s[12:13], 0, v[112:113]
	v_lshl_add_u64 v[112:113], s[26:27], 2, v[112:113]
	s_lshl_b32 s8, s48, 2
	v_lshl_add_u64 v[112:113], v[112:113], 0, s[8:9]
	global_store_dword v[112:113], v114, off
.LBB0_611:
	s_or_b64 exec, exec, s[28:29]
	v_or_b32_e32 v112, 16, v142
	v_ashrrev_i32_e32 v113, 31, v112
	v_lshlrev_b64 v[114:115], 11, v[112:113]
	v_lshl_add_u64 v[114:115], s[2:3], 0, v[114:115]
	v_lshl_add_u64 v[114:115], v[140:141], 1, v[114:115]
	s_waitcnt vmcnt(31)
	v_lshlrev_b32_e32 v118, 16, v164
	v_and_b32_e32 v119, 0xffff0000, v164
	v_lshlrev_b32_e32 v116, 16, v165
	v_and_b32_e32 v117, 0xffff0000, v165
	v_pk_add_f32 v[110:111], v[110:111], v[116:117]
	v_pk_add_f32 v[108:109], v[108:109], v[118:119]
	s_nop 0
	v_cvt_pk_bf16_f32 v116, v108, v109
	v_cvt_pk_bf16_f32 v117, v110, v111
	v_mul_f32_e32 v109, v109, v109
	global_store_dwordx2 v[114:115], v[116:117], off
	v_mul_f32_e32 v111, v111, v111
	v_fmac_f32_e32 v109, v108, v108
	v_fmac_f32_e32 v111, v110, v110
	v_add_f32_e32 v108, v109, v111
	s_waitcnt vmcnt(31)
	v_lshlrev_b32_e32 v116, 16, v166
	v_and_b32_e32 v117, 0xffff0000, v166
	v_lshlrev_b32_e32 v118, 16, v167
	v_and_b32_e32 v119, 0xffff0000, v167
	v_pk_add_f32 v[106:107], v[106:107], v[118:119]
	v_pk_add_f32 v[104:105], v[104:105], v[116:117]
	s_nop 0
	v_cvt_pk_bf16_f32 v116, v104, v105
	v_cvt_pk_bf16_f32 v117, v106, v107
	v_mul_f32_e32 v105, v105, v105
	global_store_dwordx2 v[114:115], v[116:117], off offset:32
	v_mul_f32_e32 v107, v107, v107
	v_fmac_f32_e32 v105, v104, v104
	v_fmac_f32_e32 v107, v106, v106
	v_add_f32_e32 v104, v105, v107
	v_add_f32_e32 v104, v108, v104
	s_waitcnt vmcnt(31)
	v_lshlrev_b32_e32 v116, 16, v168
	v_and_b32_e32 v117, 0xffff0000, v168
	v_lshlrev_b32_e32 v118, 16, v169
	v_and_b32_e32 v119, 0xffff0000, v169
	v_pk_add_f32 v[102:103], v[102:103], v[118:119]
	v_pk_add_f32 v[100:101], v[100:101], v[116:117]
	s_nop 0
	v_cvt_pk_bf16_f32 v116, v100, v101
	v_cvt_pk_bf16_f32 v117, v102, v103
	v_mul_f32_e32 v101, v101, v101
	v_mul_f32_e32 v103, v103, v103
	v_fmac_f32_e32 v101, v100, v100
	v_fmac_f32_e32 v103, v102, v102
	v_add_f32_e32 v100, v101, v103
	v_add_f32_e32 v104, v104, v100
	global_store_dwordx2 v[114:115], v[116:117], off offset:256
	s_waitcnt vmcnt(31)
	v_lshlrev_b32_e32 v100, 16, v170
	v_and_b32_e32 v101, 0xffff0000, v170
	v_lshlrev_b32_e32 v102, 16, v171
	v_and_b32_e32 v103, 0xffff0000, v171
	v_pk_add_f32 v[98:99], v[98:99], v[102:103]
	v_pk_add_f32 v[96:97], v[96:97], v[100:101]
	v_mul_f32_e32 v101, v99, v99
	v_mul_f32_e32 v100, v97, v97
	v_fmac_f32_e32 v100, v96, v96
	v_fmac_f32_e32 v101, v98, v98
	v_add_f32_e32 v100, v100, v101
	v_add_f32_e32 v100, v104, v100
	ds_swizzle_b32 v101, v100 offset:swizzle(SWAP,16)
	v_cvt_pk_bf16_f32 v96, v96, v97
	v_cvt_pk_bf16_f32 v97, v98, v99
	global_store_dwordx2 v[114:115], v[96:97], off offset:288
	s_waitcnt lgkmcnt(0)
	v_add_f32_e32 v96, v100, v101
	v_mov_b32_e32 v97, v96
	s_nop 1
	v_permlane32_swap_b32_e32 v96, v97
	s_and_saveexec_b64 s[28:29], s[4:5]
	s_cbranch_execz .LBB0_613
	v_add_f32_e32 v98, v96, v97
	v_lshlrev_b64 v[96:97], 6, v[112:113]
	v_lshl_add_u64 v[96:97], s[12:13], 0, v[96:97]
	v_lshl_add_u64 v[96:97], s[26:27], 2, v[96:97]
	s_lshl_b32 s8, s48, 2
	v_lshl_add_u64 v[96:97], v[96:97], 0, s[8:9]
	global_store_dword v[96:97], v98, off
.LBB0_613:
	s_or_b64 exec, exec, s[28:29]
	v_or_b32_e32 v96, 32, v142
	v_ashrrev_i32_e32 v97, 31, v96
	v_lshlrev_b64 v[98:99], 11, v[96:97]
	v_lshl_add_u64 v[98:99], s[2:3], 0, v[98:99]
	v_lshl_add_u64 v[98:99], v[140:141], 1, v[98:99]
	s_waitcnt vmcnt(31)
	v_lshlrev_b32_e32 v102, 16, v172
	v_and_b32_e32 v103, 0xffff0000, v172
	v_lshlrev_b32_e32 v100, 16, v173
	v_and_b32_e32 v101, 0xffff0000, v173
	v_pk_add_f32 v[94:95], v[94:95], v[100:101]
	v_pk_add_f32 v[92:93], v[92:93], v[102:103]
	s_nop 0
	v_cvt_pk_bf16_f32 v100, v92, v93
	v_cvt_pk_bf16_f32 v101, v94, v95
	v_mul_f32_e32 v93, v93, v93
	global_store_dwordx2 v[98:99], v[100:101], off
	v_mul_f32_e32 v95, v95, v95
	v_fmac_f32_e32 v93, v92, v92
	v_fmac_f32_e32 v95, v94, v94
	v_add_f32_e32 v92, v93, v95
	s_waitcnt vmcnt(31)
	v_lshlrev_b32_e32 v100, 16, v174
	v_and_b32_e32 v101, 0xffff0000, v174
	v_lshlrev_b32_e32 v102, 16, v175
	v_and_b32_e32 v103, 0xffff0000, v175
	v_pk_add_f32 v[90:91], v[90:91], v[102:103]
	v_pk_add_f32 v[88:89], v[88:89], v[100:101]
	s_nop 0
	v_cvt_pk_bf16_f32 v100, v88, v89
	v_cvt_pk_bf16_f32 v101, v90, v91
	v_mul_f32_e32 v89, v89, v89
	global_store_dwordx2 v[98:99], v[100:101], off offset:32
	v_mul_f32_e32 v91, v91, v91
	v_fmac_f32_e32 v89, v88, v88
	v_fmac_f32_e32 v91, v90, v90
	v_add_f32_e32 v88, v89, v91
	v_add_f32_e32 v88, v92, v88
	s_waitcnt vmcnt(31)
	v_lshlrev_b32_e32 v100, 16, v176
	v_and_b32_e32 v101, 0xffff0000, v176
	v_lshlrev_b32_e32 v102, 16, v177
	v_and_b32_e32 v103, 0xffff0000, v177
	v_pk_add_f32 v[86:87], v[86:87], v[102:103]
	v_pk_add_f32 v[84:85], v[84:85], v[100:101]
	s_nop 0
	v_cvt_pk_bf16_f32 v100, v84, v85
	v_cvt_pk_bf16_f32 v101, v86, v87
	v_mul_f32_e32 v85, v85, v85
	v_mul_f32_e32 v87, v87, v87
	v_fmac_f32_e32 v85, v84, v84
	v_fmac_f32_e32 v87, v86, v86
	v_add_f32_e32 v84, v85, v87
	v_add_f32_e32 v88, v88, v84
	global_store_dwordx2 v[98:99], v[100:101], off offset:256
	s_waitcnt vmcnt(31)
	v_lshlrev_b32_e32 v84, 16, v178
	v_and_b32_e32 v85, 0xffff0000, v178
	v_lshlrev_b32_e32 v86, 16, v179
	v_and_b32_e32 v87, 0xffff0000, v179
	v_pk_add_f32 v[82:83], v[82:83], v[86:87]
	v_pk_add_f32 v[80:81], v[80:81], v[84:85]
	v_mul_f32_e32 v85, v83, v83
	v_mul_f32_e32 v84, v81, v81
	v_fmac_f32_e32 v84, v80, v80
	v_fmac_f32_e32 v85, v82, v82
	v_add_f32_e32 v84, v84, v85
	v_add_f32_e32 v84, v88, v84
	ds_swizzle_b32 v85, v84 offset:swizzle(SWAP,16)
	v_cvt_pk_bf16_f32 v80, v80, v81
	v_cvt_pk_bf16_f32 v81, v82, v83
	global_store_dwordx2 v[98:99], v[80:81], off offset:288
	s_waitcnt lgkmcnt(0)
	v_add_f32_e32 v80, v84, v85
	v_mov_b32_e32 v81, v80
	s_nop 1
	v_permlane32_swap_b32_e32 v80, v81
	s_and_saveexec_b64 s[28:29], s[4:5]
	s_cbranch_execz .LBB0_615
	v_add_f32_e32 v82, v80, v81
	v_lshlrev_b64 v[80:81], 6, v[96:97]
	v_lshl_add_u64 v[80:81], s[12:13], 0, v[80:81]
	v_lshl_add_u64 v[80:81], s[26:27], 2, v[80:81]
	s_lshl_b32 s8, s48, 2
	v_lshl_add_u64 v[80:81], v[80:81], 0, s[8:9]
	global_store_dword v[80:81], v82, off
.LBB0_615:
	s_or_b64 exec, exec, s[28:29]
	v_or_b32_e32 v80, 48, v142
	v_ashrrev_i32_e32 v81, 31, v80
	v_lshlrev_b64 v[82:83], 11, v[80:81]
	v_lshl_add_u64 v[82:83], s[2:3], 0, v[82:83]
	v_lshl_add_u64 v[82:83], v[140:141], 1, v[82:83]
	s_waitcnt vmcnt(31)
	v_lshlrev_b32_e32 v86, 16, v180
	v_and_b32_e32 v87, 0xffff0000, v180
	v_lshlrev_b32_e32 v84, 16, v181
	v_and_b32_e32 v85, 0xffff0000, v181
	v_pk_add_f32 v[78:79], v[78:79], v[84:85]
	v_pk_add_f32 v[76:77], v[76:77], v[86:87]
	s_nop 0
	v_cvt_pk_bf16_f32 v84, v76, v77
	v_cvt_pk_bf16_f32 v85, v78, v79
	v_mul_f32_e32 v77, v77, v77
	global_store_dwordx2 v[82:83], v[84:85], off
	v_mul_f32_e32 v79, v79, v79
	v_fmac_f32_e32 v77, v76, v76
	v_fmac_f32_e32 v79, v78, v78
	v_add_f32_e32 v76, v77, v79
	s_waitcnt vmcnt(31)
	v_lshlrev_b32_e32 v84, 16, v182
	v_and_b32_e32 v85, 0xffff0000, v182
	v_lshlrev_b32_e32 v86, 16, v183
	v_and_b32_e32 v87, 0xffff0000, v183
	v_pk_add_f32 v[74:75], v[74:75], v[86:87]
	v_pk_add_f32 v[72:73], v[72:73], v[84:85]
	s_nop 0
	v_cvt_pk_bf16_f32 v84, v72, v73
	v_cvt_pk_bf16_f32 v85, v74, v75
	v_mul_f32_e32 v73, v73, v73
	global_store_dwordx2 v[82:83], v[84:85], off offset:32
	v_mul_f32_e32 v75, v75, v75
	v_fmac_f32_e32 v73, v72, v72
	v_fmac_f32_e32 v75, v74, v74
	v_add_f32_e32 v72, v73, v75
	v_add_f32_e32 v72, v76, v72
	s_waitcnt vmcnt(31)
	v_lshlrev_b32_e32 v84, 16, v184
	v_and_b32_e32 v85, 0xffff0000, v184
	v_lshlrev_b32_e32 v86, 16, v185
	v_and_b32_e32 v87, 0xffff0000, v185
	v_pk_add_f32 v[70:71], v[70:71], v[86:87]
	v_pk_add_f32 v[68:69], v[68:69], v[84:85]
	s_nop 0
	v_cvt_pk_bf16_f32 v84, v68, v69
	v_cvt_pk_bf16_f32 v85, v70, v71
	v_mul_f32_e32 v69, v69, v69
	v_mul_f32_e32 v71, v71, v71
	v_fmac_f32_e32 v69, v68, v68
	v_fmac_f32_e32 v71, v70, v70
	v_add_f32_e32 v68, v69, v71
	v_add_f32_e32 v72, v72, v68
	global_store_dwordx2 v[82:83], v[84:85], off offset:256
	s_waitcnt vmcnt(31)
	v_lshlrev_b32_e32 v68, 16, v186
	v_and_b32_e32 v69, 0xffff0000, v186
	v_lshlrev_b32_e32 v70, 16, v187
	v_and_b32_e32 v71, 0xffff0000, v187
	v_pk_add_f32 v[66:67], v[66:67], v[70:71]
	v_pk_add_f32 v[64:65], v[64:65], v[68:69]
	v_mul_f32_e32 v69, v67, v67
	v_mul_f32_e32 v68, v65, v65
	v_fmac_f32_e32 v68, v64, v64
	v_fmac_f32_e32 v69, v66, v66
	v_add_f32_e32 v68, v68, v69
	v_add_f32_e32 v68, v72, v68
	ds_swizzle_b32 v69, v68 offset:swizzle(SWAP,16)
	v_cvt_pk_bf16_f32 v64, v64, v65
	v_cvt_pk_bf16_f32 v65, v66, v67
	global_store_dwordx2 v[82:83], v[64:65], off offset:288
	s_waitcnt lgkmcnt(0)
	v_add_f32_e32 v64, v68, v69
	v_mov_b32_e32 v65, v64
	s_nop 1
	v_permlane32_swap_b32_e32 v64, v65
	s_and_saveexec_b64 s[28:29], s[4:5]
	s_cbranch_execz .LBB0_617
	v_add_f32_e32 v66, v64, v65
	v_lshlrev_b64 v[64:65], 6, v[80:81]
	v_lshl_add_u64 v[64:65], s[12:13], 0, v[64:65]
	v_lshl_add_u64 v[64:65], s[26:27], 2, v[64:65]
	s_lshl_b32 s8, s48, 2
	v_lshl_add_u64 v[64:65], v[64:65], 0, s[8:9]
	global_store_dword v[64:65], v66, off
.LBB0_617:
	s_or_b64 exec, exec, s[28:29]
	v_add_u32_e32 v64, 0x80, v142
	v_ashrrev_i32_e32 v65, 31, v64
	v_lshlrev_b64 v[66:67], 11, v[64:65]
	v_lshl_add_u64 v[66:67], s[2:3], 0, v[66:67]
	v_lshl_add_u64 v[66:67], v[140:141], 1, v[66:67]
	s_waitcnt vmcnt(31)
	v_lshlrev_b32_e32 v70, 16, v188
	v_and_b32_e32 v71, 0xffff0000, v188
	v_lshlrev_b32_e32 v68, 16, v189
	v_and_b32_e32 v69, 0xffff0000, v189
	v_pk_add_f32 v[62:63], v[62:63], v[68:69]
	v_pk_add_f32 v[60:61], v[60:61], v[70:71]
	s_nop 0
	v_cvt_pk_bf16_f32 v68, v60, v61
	v_cvt_pk_bf16_f32 v69, v62, v63
	v_mul_f32_e32 v61, v61, v61
	global_store_dwordx2 v[66:67], v[68:69], off
	v_mul_f32_e32 v63, v63, v63
	v_fmac_f32_e32 v61, v60, v60
	v_fmac_f32_e32 v63, v62, v62
	v_add_f32_e32 v60, v61, v63
	s_waitcnt vmcnt(31)
	v_lshlrev_b32_e32 v68, 16, v190
	v_and_b32_e32 v69, 0xffff0000, v190
	v_lshlrev_b32_e32 v70, 16, v191
	v_and_b32_e32 v71, 0xffff0000, v191
	v_pk_add_f32 v[58:59], v[58:59], v[70:71]
	v_pk_add_f32 v[56:57], v[56:57], v[68:69]
	s_nop 0
	v_cvt_pk_bf16_f32 v68, v56, v57
	v_cvt_pk_bf16_f32 v69, v58, v59
	v_mul_f32_e32 v57, v57, v57
	global_store_dwordx2 v[66:67], v[68:69], off offset:32
	v_mul_f32_e32 v59, v59, v59
	v_fmac_f32_e32 v57, v56, v56
	v_fmac_f32_e32 v59, v58, v58
	v_add_f32_e32 v56, v57, v59
	v_add_f32_e32 v56, v60, v56
	s_waitcnt vmcnt(31)
	v_lshlrev_b32_e32 v68, 16, v192
	v_and_b32_e32 v69, 0xffff0000, v192
	v_lshlrev_b32_e32 v70, 16, v193
	v_and_b32_e32 v71, 0xffff0000, v193
	v_pk_add_f32 v[54:55], v[54:55], v[70:71]
	v_pk_add_f32 v[52:53], v[52:53], v[68:69]
	s_nop 0
	v_cvt_pk_bf16_f32 v68, v52, v53
	v_cvt_pk_bf16_f32 v69, v54, v55
	v_mul_f32_e32 v53, v53, v53
	v_mul_f32_e32 v55, v55, v55
	v_fmac_f32_e32 v53, v52, v52
	v_fmac_f32_e32 v55, v54, v54
	v_add_f32_e32 v52, v53, v55
	v_add_f32_e32 v56, v56, v52
	global_store_dwordx2 v[66:67], v[68:69], off offset:256
	s_waitcnt vmcnt(31)
	v_lshlrev_b32_e32 v52, 16, v194
	v_and_b32_e32 v53, 0xffff0000, v194
	v_lshlrev_b32_e32 v54, 16, v195
	v_and_b32_e32 v55, 0xffff0000, v195
	v_pk_add_f32 v[50:51], v[50:51], v[54:55]
	v_pk_add_f32 v[48:49], v[48:49], v[52:53]
	v_mul_f32_e32 v53, v51, v51
	v_mul_f32_e32 v52, v49, v49
	v_fmac_f32_e32 v52, v48, v48
	v_fmac_f32_e32 v53, v50, v50
	v_add_f32_e32 v52, v52, v53
	v_add_f32_e32 v52, v56, v52
	ds_swizzle_b32 v53, v52 offset:swizzle(SWAP,16)
	v_cvt_pk_bf16_f32 v48, v48, v49
	v_cvt_pk_bf16_f32 v49, v50, v51
	global_store_dwordx2 v[66:67], v[48:49], off offset:288
	s_waitcnt lgkmcnt(0)
	v_add_f32_e32 v48, v52, v53
	v_mov_b32_e32 v49, v48
	s_nop 1
	v_permlane32_swap_b32_e32 v48, v49
	s_and_saveexec_b64 s[28:29], s[4:5]
	s_cbranch_execz .LBB0_619
	v_add_f32_e32 v50, v48, v49
	v_lshlrev_b64 v[48:49], 6, v[64:65]
	v_lshl_add_u64 v[48:49], s[12:13], 0, v[48:49]
	v_lshl_add_u64 v[48:49], s[26:27], 2, v[48:49]
	s_lshl_b32 s8, s48, 2
	v_lshl_add_u64 v[48:49], v[48:49], 0, s[8:9]
	global_store_dword v[48:49], v50, off
.LBB0_619:
	s_or_b64 exec, exec, s[28:29]
	v_add_u32_e32 v48, 0x90, v142
	v_ashrrev_i32_e32 v49, 31, v48
	v_lshlrev_b64 v[50:51], 11, v[48:49]
	v_lshl_add_u64 v[50:51], s[2:3], 0, v[50:51]
	v_lshl_add_u64 v[50:51], v[140:141], 1, v[50:51]
	s_waitcnt vmcnt(31)
	v_lshlrev_b32_e32 v54, 16, v196
	v_and_b32_e32 v55, 0xffff0000, v196
	v_lshlrev_b32_e32 v52, 16, v197
	v_and_b32_e32 v53, 0xffff0000, v197
	v_pk_add_f32 v[46:47], v[46:47], v[52:53]
	v_pk_add_f32 v[44:45], v[44:45], v[54:55]
	s_nop 0
	v_cvt_pk_bf16_f32 v52, v44, v45
	v_cvt_pk_bf16_f32 v53, v46, v47
	v_mul_f32_e32 v45, v45, v45
	global_store_dwordx2 v[50:51], v[52:53], off
	v_mul_f32_e32 v47, v47, v47
	v_fmac_f32_e32 v45, v44, v44
	v_fmac_f32_e32 v47, v46, v46
	v_add_f32_e32 v44, v45, v47
	s_waitcnt vmcnt(31)
	v_lshlrev_b32_e32 v52, 16, v198
	v_and_b32_e32 v53, 0xffff0000, v198
	v_lshlrev_b32_e32 v54, 16, v199
	v_and_b32_e32 v55, 0xffff0000, v199
	v_pk_add_f32 v[42:43], v[42:43], v[54:55]
	v_pk_add_f32 v[40:41], v[40:41], v[52:53]
	s_nop 0
	v_cvt_pk_bf16_f32 v52, v40, v41
	v_cvt_pk_bf16_f32 v53, v42, v43
	v_mul_f32_e32 v41, v41, v41
	global_store_dwordx2 v[50:51], v[52:53], off offset:32
	v_mul_f32_e32 v43, v43, v43
	v_fmac_f32_e32 v41, v40, v40
	v_fmac_f32_e32 v43, v42, v42
	v_add_f32_e32 v40, v41, v43
	v_add_f32_e32 v40, v44, v40
	s_waitcnt vmcnt(31)
	v_lshlrev_b32_e32 v52, 16, v200
	v_and_b32_e32 v53, 0xffff0000, v200
	v_lshlrev_b32_e32 v54, 16, v201
	v_and_b32_e32 v55, 0xffff0000, v201
	v_pk_add_f32 v[38:39], v[38:39], v[54:55]
	v_pk_add_f32 v[36:37], v[36:37], v[52:53]
	s_nop 0
	v_cvt_pk_bf16_f32 v52, v36, v37
	v_cvt_pk_bf16_f32 v53, v38, v39
	v_mul_f32_e32 v37, v37, v37
	v_mul_f32_e32 v39, v39, v39
	v_fmac_f32_e32 v37, v36, v36
	v_fmac_f32_e32 v39, v38, v38
	v_add_f32_e32 v36, v37, v39
	v_add_f32_e32 v40, v40, v36
	global_store_dwordx2 v[50:51], v[52:53], off offset:256
	s_waitcnt vmcnt(31)
	v_lshlrev_b32_e32 v36, 16, v202
	v_and_b32_e32 v37, 0xffff0000, v202
	v_lshlrev_b32_e32 v38, 16, v203
	v_and_b32_e32 v39, 0xffff0000, v203
	v_pk_add_f32 v[34:35], v[34:35], v[38:39]
	v_pk_add_f32 v[32:33], v[32:33], v[36:37]
	v_mul_f32_e32 v37, v35, v35
	v_mul_f32_e32 v36, v33, v33
	v_fmac_f32_e32 v36, v32, v32
	v_fmac_f32_e32 v37, v34, v34
	v_add_f32_e32 v36, v36, v37
	v_add_f32_e32 v36, v40, v36
	ds_swizzle_b32 v37, v36 offset:swizzle(SWAP,16)
	v_cvt_pk_bf16_f32 v32, v32, v33
	v_cvt_pk_bf16_f32 v33, v34, v35
	global_store_dwordx2 v[50:51], v[32:33], off offset:288
	s_waitcnt lgkmcnt(0)
	v_add_f32_e32 v32, v36, v37
	v_mov_b32_e32 v33, v32
	s_nop 1
	v_permlane32_swap_b32_e32 v32, v33
	s_and_saveexec_b64 s[28:29], s[4:5]
	s_cbranch_execz .LBB0_621
	v_add_f32_e32 v34, v32, v33
	v_lshlrev_b64 v[32:33], 6, v[48:49]
	v_lshl_add_u64 v[32:33], s[12:13], 0, v[32:33]
	v_lshl_add_u64 v[32:33], s[26:27], 2, v[32:33]
	s_lshl_b32 s8, s48, 2
	v_lshl_add_u64 v[32:33], v[32:33], 0, s[8:9]
	global_store_dword v[32:33], v34, off
.LBB0_621:
	s_or_b64 exec, exec, s[28:29]
	v_add_u32_e32 v32, 0xa0, v142
	v_ashrrev_i32_e32 v33, 31, v32
	v_lshlrev_b64 v[34:35], 11, v[32:33]
	v_lshl_add_u64 v[34:35], s[2:3], 0, v[34:35]
	v_lshl_add_u64 v[34:35], v[140:141], 1, v[34:35]
	s_waitcnt vmcnt(31)
	v_lshlrev_b32_e32 v38, 16, v204
	v_and_b32_e32 v39, 0xffff0000, v204
	v_lshlrev_b32_e32 v36, 16, v205
	v_and_b32_e32 v37, 0xffff0000, v205
	v_pk_add_f32 v[30:31], v[30:31], v[36:37]
	v_pk_add_f32 v[28:29], v[28:29], v[38:39]
	s_nop 0
	v_cvt_pk_bf16_f32 v36, v28, v29
	v_cvt_pk_bf16_f32 v37, v30, v31
	v_mul_f32_e32 v29, v29, v29
	global_store_dwordx2 v[34:35], v[36:37], off
	v_mul_f32_e32 v31, v31, v31
	v_fmac_f32_e32 v29, v28, v28
	v_fmac_f32_e32 v31, v30, v30
	v_add_f32_e32 v28, v29, v31
	s_waitcnt vmcnt(31)
	v_lshlrev_b32_e32 v36, 16, v208
	v_and_b32_e32 v37, 0xffff0000, v208
	v_lshlrev_b32_e32 v38, 16, v209
	v_and_b32_e32 v39, 0xffff0000, v209
	v_pk_add_f32 v[26:27], v[26:27], v[38:39]
	v_pk_add_f32 v[24:25], v[24:25], v[36:37]
	s_nop 0
	v_cvt_pk_bf16_f32 v36, v24, v25
	v_cvt_pk_bf16_f32 v37, v26, v27
	v_mul_f32_e32 v25, v25, v25
	global_store_dwordx2 v[34:35], v[36:37], off offset:32
	v_mul_f32_e32 v27, v27, v27
	v_fmac_f32_e32 v25, v24, v24
	v_fmac_f32_e32 v27, v26, v26
	v_add_f32_e32 v24, v25, v27
	v_add_f32_e32 v24, v28, v24
	s_waitcnt vmcnt(31)
	v_lshlrev_b32_e32 v36, 16, v210
	v_and_b32_e32 v37, 0xffff0000, v210
	v_lshlrev_b32_e32 v38, 16, v211
	v_and_b32_e32 v39, 0xffff0000, v211
	v_pk_add_f32 v[22:23], v[22:23], v[38:39]
	v_pk_add_f32 v[20:21], v[20:21], v[36:37]
	s_nop 0
	v_cvt_pk_bf16_f32 v36, v20, v21
	v_cvt_pk_bf16_f32 v37, v22, v23
	v_mul_f32_e32 v21, v21, v21
	v_mul_f32_e32 v23, v23, v23
	v_fmac_f32_e32 v21, v20, v20
	v_fmac_f32_e32 v23, v22, v22
	v_add_f32_e32 v20, v21, v23
	v_add_f32_e32 v24, v24, v20
	global_store_dwordx2 v[34:35], v[36:37], off offset:256
	s_waitcnt vmcnt(31)
	v_lshlrev_b32_e32 v20, 16, v212
	v_and_b32_e32 v21, 0xffff0000, v212
	v_lshlrev_b32_e32 v22, 16, v213
	v_and_b32_e32 v23, 0xffff0000, v213
	v_pk_add_f32 v[18:19], v[18:19], v[22:23]
	v_pk_add_f32 v[16:17], v[16:17], v[20:21]
	v_mul_f32_e32 v21, v19, v19
	v_mul_f32_e32 v20, v17, v17
	v_fmac_f32_e32 v20, v16, v16
	v_fmac_f32_e32 v21, v18, v18
	v_add_f32_e32 v20, v20, v21
	v_add_f32_e32 v20, v24, v20
	ds_swizzle_b32 v21, v20 offset:swizzle(SWAP,16)
	v_cvt_pk_bf16_f32 v16, v16, v17
	v_cvt_pk_bf16_f32 v17, v18, v19
	global_store_dwordx2 v[34:35], v[16:17], off offset:288
	s_waitcnt lgkmcnt(0)
	v_add_f32_e32 v16, v20, v21
	v_mov_b32_e32 v17, v16
	s_nop 1
	v_permlane32_swap_b32_e32 v16, v17
	s_and_saveexec_b64 s[28:29], s[4:5]
	s_cbranch_execz .LBB0_623
	v_add_f32_e32 v18, v16, v17
	v_lshlrev_b64 v[16:17], 6, v[32:33]
	v_lshl_add_u64 v[16:17], s[12:13], 0, v[16:17]
	v_lshl_add_u64 v[16:17], s[26:27], 2, v[16:17]
	s_lshl_b32 s8, s48, 2
	v_lshl_add_u64 v[16:17], v[16:17], 0, s[8:9]
	global_store_dword v[16:17], v18, off
.LBB0_623:
	s_or_b64 exec, exec, s[28:29]
	v_add_u32_e32 v16, 0xb0, v142
	v_ashrrev_i32_e32 v17, 31, v16
	v_lshlrev_b64 v[18:19], 11, v[16:17]
	v_lshl_add_u64 v[18:19], s[2:3], 0, v[18:19]
	v_lshl_add_u64 v[18:19], v[140:141], 1, v[18:19]
	s_waitcnt vmcnt(31)
	v_lshlrev_b32_e32 v22, 16, v214
	v_and_b32_e32 v23, 0xffff0000, v214
	v_lshlrev_b32_e32 v20, 16, v215
	v_and_b32_e32 v21, 0xffff0000, v215
	v_pk_add_f32 v[14:15], v[14:15], v[20:21]
	v_pk_add_f32 v[12:13], v[12:13], v[22:23]
	s_nop 0
	v_cvt_pk_bf16_f32 v20, v12, v13
	v_cvt_pk_bf16_f32 v21, v14, v15
	v_mul_f32_e32 v13, v13, v13
	global_store_dwordx2 v[18:19], v[20:21], off
	v_mul_f32_e32 v15, v15, v15
	v_fmac_f32_e32 v13, v12, v12
	v_fmac_f32_e32 v15, v14, v14
	v_add_f32_e32 v12, v13, v15
	s_waitcnt vmcnt(31)
	v_lshlrev_b32_e32 v20, 16, v216
	v_and_b32_e32 v21, 0xffff0000, v216
	v_lshlrev_b32_e32 v22, 16, v217
	v_and_b32_e32 v23, 0xffff0000, v217
	v_pk_add_f32 v[10:11], v[10:11], v[22:23]
	v_pk_add_f32 v[8:9], v[8:9], v[20:21]
	s_nop 0
	v_cvt_pk_bf16_f32 v20, v8, v9
	v_cvt_pk_bf16_f32 v21, v10, v11
	v_mul_f32_e32 v9, v9, v9
	global_store_dwordx2 v[18:19], v[20:21], off offset:32
	v_mul_f32_e32 v11, v11, v11
	v_fmac_f32_e32 v9, v8, v8
	v_fmac_f32_e32 v11, v10, v10
	v_add_f32_e32 v8, v9, v11
	v_add_f32_e32 v8, v12, v8
	s_waitcnt vmcnt(31)
	v_lshlrev_b32_e32 v20, 16, v218
	v_and_b32_e32 v21, 0xffff0000, v218
	v_lshlrev_b32_e32 v22, 16, v219
	v_and_b32_e32 v23, 0xffff0000, v219
	v_pk_add_f32 v[6:7], v[6:7], v[22:23]
	v_pk_add_f32 v[4:5], v[4:5], v[20:21]
	s_nop 0
	v_cvt_pk_bf16_f32 v20, v4, v5
	v_cvt_pk_bf16_f32 v21, v6, v7
	v_mul_f32_e32 v5, v5, v5
	v_mul_f32_e32 v7, v7, v7
	v_fmac_f32_e32 v5, v4, v4
	v_fmac_f32_e32 v7, v6, v6
	v_add_f32_e32 v4, v5, v7
	v_add_f32_e32 v8, v8, v4
	global_store_dwordx2 v[18:19], v[20:21], off offset:256
	s_waitcnt vmcnt(31)
	v_lshlrev_b32_e32 v4, 16, v220
	v_and_b32_e32 v5, 0xffff0000, v220
	v_lshlrev_b32_e32 v6, 16, v221
	v_and_b32_e32 v7, 0xffff0000, v221
	v_pk_add_f32 v[2:3], v[2:3], v[6:7]
	v_pk_add_f32 v[0:1], v[0:1], v[4:5]
	v_mul_f32_e32 v5, v3, v3
	v_mul_f32_e32 v4, v1, v1
	v_fmac_f32_e32 v4, v0, v0
	v_fmac_f32_e32 v5, v2, v2
	v_add_f32_e32 v4, v4, v5
	v_add_f32_e32 v4, v8, v4
	ds_swizzle_b32 v5, v4 offset:swizzle(SWAP,16)
	v_cvt_pk_bf16_f32 v0, v0, v1
	v_cvt_pk_bf16_f32 v1, v2, v3
	global_store_dwordx2 v[18:19], v[0:1], off offset:288
	s_waitcnt lgkmcnt(0)
	v_add_f32_e32 v0, v4, v5
	v_mov_b32_e32 v1, v0
	s_nop 1
	v_permlane32_swap_b32_e32 v0, v1
	s_and_saveexec_b64 s[28:29], s[4:5]
	s_cbranch_execz .LBB0_625
	v_add_f32_e32 v2, v0, v1
	v_lshlrev_b64 v[0:1], 6, v[16:17]
	v_lshl_add_u64 v[0:1], s[12:13], 0, v[0:1]
	v_lshl_add_u64 v[0:1], s[26:27], 2, v[0:1]
	s_lshl_b32 s8, s48, 2
	v_lshl_add_u64 v[0:1], v[0:1], 0, s[8:9]
	global_store_dword v[0:1], v2, off

.LBB0_781:
	v_lshl_add_u32 v142, s26, 8, v144
	v_ashrrev_i32_e32 v143, 31, v142
	v_lshl_or_b32 v140, s10, 8, v146
	v_lshlrev_b64 v[150:151], 11, v[142:143]
	v_ashrrev_i32_e32 v141, 31, v140
	v_lshl_add_u64 v[150:151], s[8:9], 0, v[150:151]
	v_lshl_add_u64 v[150:151], v[140:141], 1, v[150:151]
	s_mov_b64 s[98:99], 0x8000
	s_mov_b64 s[100:101], 0x28000
	global_load_dwordx2 v[156:157], v[150:151], off
	global_load_dwordx2 v[158:159], v[150:151], off offset:32
	global_load_dwordx2 v[160:161], v[150:151], off offset:256
	global_load_dwordx2 v[162:163], v[150:151], off offset:288
	v_lshl_add_u64 v[222:223], v[150:151], 0, s[98:99]
	global_load_dwordx2 v[164:165], v[222:223], off
	global_load_dwordx2 v[166:167], v[222:223], off offset:32
	global_load_dwordx2 v[168:169], v[222:223], off offset:256
	global_load_dwordx2 v[170:171], v[222:223], off offset:288
	v_lshl_add_u64 v[222:223], v[222:223], 0, s[98:99]
	global_load_dwordx2 v[172:173], v[222:223], off
	global_load_dwordx2 v[174:175], v[222:223], off offset:32
	global_load_dwordx2 v[176:177], v[222:223], off offset:256
	global_load_dwordx2 v[178:179], v[222:223], off offset:288
	v_lshl_add_u64 v[222:223], v[222:223], 0, s[98:99]
	global_load_dwordx2 v[180:181], v[222:223], off
	global_load_dwordx2 v[182:183], v[222:223], off offset:32
	global_load_dwordx2 v[184:185], v[222:223], off offset:256
	global_load_dwordx2 v[186:187], v[222:223], off offset:288
	v_lshl_add_u64 v[222:223], v[222:223], 0, s[100:101]
	global_load_dwordx2 v[188:189], v[222:223], off
	global_load_dwordx2 v[190:191], v[222:223], off offset:32
	global_load_dwordx2 v[192:193], v[222:223], off offset:256
	global_load_dwordx2 v[194:195], v[222:223], off offset:288
	v_lshl_add_u64 v[222:223], v[222:223], 0, s[98:99]
	global_load_dwordx2 v[196:197], v[222:223], off
	global_load_dwordx2 v[198:199], v[222:223], off offset:32
	global_load_dwordx2 v[200:201], v[222:223], off offset:256
	global_load_dwordx2 v[202:203], v[222:223], off offset:288
	v_lshl_add_u64 v[222:223], v[222:223], 0, s[98:99]
	global_load_dwordx2 v[204:205], v[222:223], off
	global_load_dwordx2 v[208:209], v[222:223], off offset:32
	global_load_dwordx2 v[210:211], v[222:223], off offset:256
	global_load_dwordx2 v[212:213], v[222:223], off offset:288
	v_lshl_add_u64 v[222:223], v[222:223], 0, s[98:99]
	global_load_dwordx2 v[214:215], v[222:223], off
	global_load_dwordx2 v[216:217], v[222:223], off offset:32
	global_load_dwordx2 v[218:219], v[222:223], off offset:256
	global_load_dwordx2 v[220:221], v[222:223], off offset:288
	s_lshl_b32 s26, s10, 2
	s_ashr_i32 s27, s26, 31
	s_waitcnt vmcnt(31)
	v_lshlrev_b32_e32 v154, 16, v156
	v_and_b32_e32 v155, 0xffff0000, v156
	v_lshlrev_b32_e32 v152, 16, v157
	v_and_b32_e32 v153, 0xffff0000, v157
	v_pk_add_f32 v[126:127], v[126:127], v[152:153]
	v_pk_add_f32 v[124:125], v[124:125], v[154:155]
	s_nop 0
	v_cvt_pk_bf16_f32 v152, v124, v125
	v_cvt_pk_bf16_f32 v153, v126, v127
	v_mul_f32_e32 v125, v125, v125
	global_store_dwordx2 v[150:151], v[152:153], off
	v_mul_f32_e32 v127, v127, v127
	v_fmac_f32_e32 v125, v124, v124
	v_fmac_f32_e32 v127, v126, v126
	v_add_f32_e32 v124, v125, v127
	s_waitcnt vmcnt(31)
	v_lshlrev_b32_e32 v152, 16, v158
	v_and_b32_e32 v153, 0xffff0000, v158
	v_lshlrev_b32_e32 v154, 16, v159
	v_and_b32_e32 v155, 0xffff0000, v159
	v_pk_add_f32 v[122:123], v[122:123], v[154:155]
	v_pk_add_f32 v[120:121], v[120:121], v[152:153]
	s_nop 0
	v_cvt_pk_bf16_f32 v152, v120, v121
	v_cvt_pk_bf16_f32 v153, v122, v123
	v_mul_f32_e32 v121, v121, v121
	global_store_dwordx2 v[150:151], v[152:153], off offset:32
	v_mul_f32_e32 v123, v123, v123
	v_fmac_f32_e32 v121, v120, v120
	v_fmac_f32_e32 v123, v122, v122
	v_add_f32_e32 v120, v121, v123
	v_add_f32_e32 v120, v124, v120
	s_waitcnt vmcnt(31)
	v_lshlrev_b32_e32 v152, 16, v160
	v_and_b32_e32 v153, 0xffff0000, v160
	v_lshlrev_b32_e32 v154, 16, v161
	v_and_b32_e32 v155, 0xffff0000, v161
	v_pk_add_f32 v[118:119], v[118:119], v[154:155]
	v_pk_add_f32 v[116:117], v[116:117], v[152:153]
	s_nop 0
	v_cvt_pk_bf16_f32 v152, v116, v117
	v_cvt_pk_bf16_f32 v153, v118, v119
	v_mul_f32_e32 v117, v117, v117
	v_mul_f32_e32 v119, v119, v119
	v_fmac_f32_e32 v117, v116, v116
	v_fmac_f32_e32 v119, v118, v118
	v_add_f32_e32 v116, v117, v119
	v_add_f32_e32 v120, v120, v116
	global_store_dwordx2 v[150:151], v[152:153], off offset:256
	s_waitcnt vmcnt(31)
	v_lshlrev_b32_e32 v116, 16, v162
	v_and_b32_e32 v117, 0xffff0000, v162
	v_lshlrev_b32_e32 v118, 16, v163
	v_and_b32_e32 v119, 0xffff0000, v163
	v_pk_add_f32 v[114:115], v[114:115], v[118:119]
	v_pk_add_f32 v[112:113], v[112:113], v[116:117]
	v_mul_f32_e32 v117, v115, v115
	v_mul_f32_e32 v116, v113, v113
	v_fmac_f32_e32 v116, v112, v112
	v_fmac_f32_e32 v117, v114, v114
	v_add_f32_e32 v116, v116, v117
	v_add_f32_e32 v116, v120, v116
	ds_swizzle_b32 v117, v116 offset:swizzle(SWAP,16)
	v_cvt_pk_bf16_f32 v112, v112, v113
	v_cvt_pk_bf16_f32 v113, v114, v115
	global_store_dwordx2 v[150:151], v[112:113], off offset:288
	s_waitcnt lgkmcnt(0)
	v_add_f32_e32 v112, v116, v117
	v_mov_b32_e32 v113, v112
	s_nop 1
	v_permlane32_swap_b32_e32 v112, v113
	s_and_saveexec_b64 s[28:29], s[4:5]
	s_cbranch_execz .LBB0_783
	v_add_f32_e32 v114, v112, v113
	v_lshlrev_b64 v[112:113], 6, v[142:143]
	v_lshl_add_u64 v[112:113], s[2:3], 0, v[112:113]
	v_lshl_add_u64 v[112:113], s[26:27], 2, v[112:113]
	s_lshl_b32 s10, s48, 2
	v_lshl_add_u64 v[112:113], v[112:113], 0, s[10:11]
	global_store_dword v[112:113], v114, off
.LBB0_783:
	s_or_b64 exec, exec, s[28:29]
	v_or_b32_e32 v112, 16, v142
	v_ashrrev_i32_e32 v113, 31, v112
	v_lshlrev_b64 v[114:115], 11, v[112:113]
	v_lshl_add_u64 v[114:115], s[8:9], 0, v[114:115]
	v_lshl_add_u64 v[114:115], v[140:141], 1, v[114:115]
	s_waitcnt vmcnt(31)
	v_lshlrev_b32_e32 v118, 16, v164
	v_and_b32_e32 v119, 0xffff0000, v164
	v_lshlrev_b32_e32 v116, 16, v165
	v_and_b32_e32 v117, 0xffff0000, v165
	v_pk_add_f32 v[110:111], v[110:111], v[116:117]
	v_pk_add_f32 v[108:109], v[108:109], v[118:119]
	s_nop 0
	v_cvt_pk_bf16_f32 v116, v108, v109
	v_cvt_pk_bf16_f32 v117, v110, v111
	v_mul_f32_e32 v109, v109, v109
	global_store_dwordx2 v[114:115], v[116:117], off
	v_mul_f32_e32 v111, v111, v111
	v_fmac_f32_e32 v109, v108, v108
	v_fmac_f32_e32 v111, v110, v110
	v_add_f32_e32 v108, v109, v111
	s_waitcnt vmcnt(31)
	v_lshlrev_b32_e32 v116, 16, v166
	v_and_b32_e32 v117, 0xffff0000, v166
	v_lshlrev_b32_e32 v118, 16, v167
	v_and_b32_e32 v119, 0xffff0000, v167
	v_pk_add_f32 v[106:107], v[106:107], v[118:119]
	v_pk_add_f32 v[104:105], v[104:105], v[116:117]
	s_nop 0
	v_cvt_pk_bf16_f32 v116, v104, v105
	v_cvt_pk_bf16_f32 v117, v106, v107
	v_mul_f32_e32 v105, v105, v105
	global_store_dwordx2 v[114:115], v[116:117], off offset:32
	v_mul_f32_e32 v107, v107, v107
	v_fmac_f32_e32 v105, v104, v104
	v_fmac_f32_e32 v107, v106, v106
	v_add_f32_e32 v104, v105, v107
	v_add_f32_e32 v104, v108, v104
	s_waitcnt vmcnt(31)
	v_lshlrev_b32_e32 v116, 16, v168
	v_and_b32_e32 v117, 0xffff0000, v168
	v_lshlrev_b32_e32 v118, 16, v169
	v_and_b32_e32 v119, 0xffff0000, v169
	v_pk_add_f32 v[102:103], v[102:103], v[118:119]
	v_pk_add_f32 v[100:101], v[100:101], v[116:117]
	s_nop 0
	v_cvt_pk_bf16_f32 v116, v100, v101
	v_cvt_pk_bf16_f32 v117, v102, v103
	v_mul_f32_e32 v101, v101, v101
	v_mul_f32_e32 v103, v103, v103
	v_fmac_f32_e32 v101, v100, v100
	v_fmac_f32_e32 v103, v102, v102
	v_add_f32_e32 v100, v101, v103
	v_add_f32_e32 v104, v104, v100
	global_store_dwordx2 v[114:115], v[116:117], off offset:256
	s_waitcnt vmcnt(31)
	v_lshlrev_b32_e32 v100, 16, v170
	v_and_b32_e32 v101, 0xffff0000, v170
	v_lshlrev_b32_e32 v102, 16, v171
	v_and_b32_e32 v103, 0xffff0000, v171
	v_pk_add_f32 v[98:99], v[98:99], v[102:103]
	v_pk_add_f32 v[96:97], v[96:97], v[100:101]
	v_mul_f32_e32 v101, v99, v99
	v_mul_f32_e32 v100, v97, v97
	v_fmac_f32_e32 v100, v96, v96
	v_fmac_f32_e32 v101, v98, v98
	v_add_f32_e32 v100, v100, v101
	v_add_f32_e32 v100, v104, v100
	ds_swizzle_b32 v101, v100 offset:swizzle(SWAP,16)
	v_cvt_pk_bf16_f32 v96, v96, v97
	v_cvt_pk_bf16_f32 v97, v98, v99
	global_store_dwordx2 v[114:115], v[96:97], off offset:288
	s_waitcnt lgkmcnt(0)
	v_add_f32_e32 v96, v100, v101
	v_mov_b32_e32 v97, v96
	s_nop 1
	v_permlane32_swap_b32_e32 v96, v97
	s_and_saveexec_b64 s[28:29], s[4:5]
	s_cbranch_execz .LBB0_785
	v_add_f32_e32 v98, v96, v97
	v_lshlrev_b64 v[96:97], 6, v[112:113]
	v_lshl_add_u64 v[96:97], s[2:3], 0, v[96:97]
	v_lshl_add_u64 v[96:97], s[26:27], 2, v[96:97]
	s_lshl_b32 s10, s48, 2
	v_lshl_add_u64 v[96:97], v[96:97], 0, s[10:11]
	global_store_dword v[96:97], v98, off
.LBB0_785:
	s_or_b64 exec, exec, s[28:29]
	v_or_b32_e32 v96, 32, v142
	v_ashrrev_i32_e32 v97, 31, v96
	v_lshlrev_b64 v[98:99], 11, v[96:97]
	v_lshl_add_u64 v[98:99], s[8:9], 0, v[98:99]
	v_lshl_add_u64 v[98:99], v[140:141], 1, v[98:99]
	s_waitcnt vmcnt(31)
	v_lshlrev_b32_e32 v102, 16, v172
	v_and_b32_e32 v103, 0xffff0000, v172
	v_lshlrev_b32_e32 v100, 16, v173
	v_and_b32_e32 v101, 0xffff0000, v173
	v_pk_add_f32 v[94:95], v[94:95], v[100:101]
	v_pk_add_f32 v[92:93], v[92:93], v[102:103]
	s_nop 0
	v_cvt_pk_bf16_f32 v100, v92, v93
	v_cvt_pk_bf16_f32 v101, v94, v95
	v_mul_f32_e32 v93, v93, v93
	global_store_dwordx2 v[98:99], v[100:101], off
	v_mul_f32_e32 v95, v95, v95
	v_fmac_f32_e32 v93, v92, v92
	v_fmac_f32_e32 v95, v94, v94
	v_add_f32_e32 v92, v93, v95
	s_waitcnt vmcnt(31)
	v_lshlrev_b32_e32 v100, 16, v174
	v_and_b32_e32 v101, 0xffff0000, v174
	v_lshlrev_b32_e32 v102, 16, v175
	v_and_b32_e32 v103, 0xffff0000, v175
	v_pk_add_f32 v[90:91], v[90:91], v[102:103]
	v_pk_add_f32 v[88:89], v[88:89], v[100:101]
	s_nop 0
	v_cvt_pk_bf16_f32 v100, v88, v89
	v_cvt_pk_bf16_f32 v101, v90, v91
	v_mul_f32_e32 v89, v89, v89
	global_store_dwordx2 v[98:99], v[100:101], off offset:32
	v_mul_f32_e32 v91, v91, v91
	v_fmac_f32_e32 v89, v88, v88
	v_fmac_f32_e32 v91, v90, v90
	v_add_f32_e32 v88, v89, v91
	v_add_f32_e32 v88, v92, v88
	s_waitcnt vmcnt(31)
	v_lshlrev_b32_e32 v100, 16, v176
	v_and_b32_e32 v101, 0xffff0000, v176
	v_lshlrev_b32_e32 v102, 16, v177
	v_and_b32_e32 v103, 0xffff0000, v177
	v_pk_add_f32 v[86:87], v[86:87], v[102:103]
	v_pk_add_f32 v[84:85], v[84:85], v[100:101]
	s_nop 0
	v_cvt_pk_bf16_f32 v100, v84, v85
	v_cvt_pk_bf16_f32 v101, v86, v87
	v_mul_f32_e32 v85, v85, v85
	v_mul_f32_e32 v87, v87, v87
	v_fmac_f32_e32 v85, v84, v84
	v_fmac_f32_e32 v87, v86, v86
	v_add_f32_e32 v84, v85, v87
	v_add_f32_e32 v88, v88, v84
	global_store_dwordx2 v[98:99], v[100:101], off offset:256
	s_waitcnt vmcnt(31)
	v_lshlrev_b32_e32 v84, 16, v178
	v_and_b32_e32 v85, 0xffff0000, v178
	v_lshlrev_b32_e32 v86, 16, v179
	v_and_b32_e32 v87, 0xffff0000, v179
	v_pk_add_f32 v[82:83], v[82:83], v[86:87]
	v_pk_add_f32 v[80:81], v[80:81], v[84:85]
	v_mul_f32_e32 v85, v83, v83
	v_mul_f32_e32 v84, v81, v81
	v_fmac_f32_e32 v84, v80, v80
	v_fmac_f32_e32 v85, v82, v82
	v_add_f32_e32 v84, v84, v85
	v_add_f32_e32 v84, v88, v84
	ds_swizzle_b32 v85, v84 offset:swizzle(SWAP,16)
	v_cvt_pk_bf16_f32 v80, v80, v81
	v_cvt_pk_bf16_f32 v81, v82, v83
	global_store_dwordx2 v[98:99], v[80:81], off offset:288
	s_waitcnt lgkmcnt(0)
	v_add_f32_e32 v80, v84, v85
	v_mov_b32_e32 v81, v80
	s_nop 1
	v_permlane32_swap_b32_e32 v80, v81
	s_and_saveexec_b64 s[28:29], s[4:5]
	s_cbranch_execz .LBB0_787
	v_add_f32_e32 v82, v80, v81
	v_lshlrev_b64 v[80:81], 6, v[96:97]
	v_lshl_add_u64 v[80:81], s[2:3], 0, v[80:81]
	v_lshl_add_u64 v[80:81], s[26:27], 2, v[80:81]
	s_lshl_b32 s10, s48, 2
	v_lshl_add_u64 v[80:81], v[80:81], 0, s[10:11]
	global_store_dword v[80:81], v82, off
.LBB0_787:
	s_or_b64 exec, exec, s[28:29]
	v_or_b32_e32 v80, 48, v142
	v_ashrrev_i32_e32 v81, 31, v80
	v_lshlrev_b64 v[82:83], 11, v[80:81]
	v_lshl_add_u64 v[82:83], s[8:9], 0, v[82:83]
	v_lshl_add_u64 v[82:83], v[140:141], 1, v[82:83]
	s_waitcnt vmcnt(31)
	v_lshlrev_b32_e32 v86, 16, v180
	v_and_b32_e32 v87, 0xffff0000, v180
	v_lshlrev_b32_e32 v84, 16, v181
	v_and_b32_e32 v85, 0xffff0000, v181
	v_pk_add_f32 v[78:79], v[78:79], v[84:85]
	v_pk_add_f32 v[76:77], v[76:77], v[86:87]
	s_nop 0
	v_cvt_pk_bf16_f32 v84, v76, v77
	v_cvt_pk_bf16_f32 v85, v78, v79
	v_mul_f32_e32 v77, v77, v77
	global_store_dwordx2 v[82:83], v[84:85], off
	v_mul_f32_e32 v79, v79, v79
	v_fmac_f32_e32 v77, v76, v76
	v_fmac_f32_e32 v79, v78, v78
	v_add_f32_e32 v76, v77, v79
	s_waitcnt vmcnt(31)
	v_lshlrev_b32_e32 v84, 16, v182
	v_and_b32_e32 v85, 0xffff0000, v182
	v_lshlrev_b32_e32 v86, 16, v183
	v_and_b32_e32 v87, 0xffff0000, v183
	v_pk_add_f32 v[74:75], v[74:75], v[86:87]
	v_pk_add_f32 v[72:73], v[72:73], v[84:85]
	s_nop 0
	v_cvt_pk_bf16_f32 v84, v72, v73
	v_cvt_pk_bf16_f32 v85, v74, v75
	v_mul_f32_e32 v73, v73, v73
	global_store_dwordx2 v[82:83], v[84:85], off offset:32
	v_mul_f32_e32 v75, v75, v75
	v_fmac_f32_e32 v73, v72, v72
	v_fmac_f32_e32 v75, v74, v74
	v_add_f32_e32 v72, v73, v75
	v_add_f32_e32 v72, v76, v72
	s_waitcnt vmcnt(31)
	v_lshlrev_b32_e32 v84, 16, v184
	v_and_b32_e32 v85, 0xffff0000, v184
	v_lshlrev_b32_e32 v86, 16, v185
	v_and_b32_e32 v87, 0xffff0000, v185
	v_pk_add_f32 v[70:71], v[70:71], v[86:87]
	v_pk_add_f32 v[68:69], v[68:69], v[84:85]
	s_nop 0
	v_cvt_pk_bf16_f32 v84, v68, v69
	v_cvt_pk_bf16_f32 v85, v70, v71
	v_mul_f32_e32 v69, v69, v69
	v_mul_f32_e32 v71, v71, v71
	v_fmac_f32_e32 v69, v68, v68
	v_fmac_f32_e32 v71, v70, v70
	v_add_f32_e32 v68, v69, v71
	v_add_f32_e32 v72, v72, v68
	global_store_dwordx2 v[82:83], v[84:85], off offset:256
	s_waitcnt vmcnt(31)
	v_lshlrev_b32_e32 v68, 16, v186
	v_and_b32_e32 v69, 0xffff0000, v186
	v_lshlrev_b32_e32 v70, 16, v187
	v_and_b32_e32 v71, 0xffff0000, v187
	v_pk_add_f32 v[66:67], v[66:67], v[70:71]
	v_pk_add_f32 v[64:65], v[64:65], v[68:69]
	v_mul_f32_e32 v69, v67, v67
	v_mul_f32_e32 v68, v65, v65
	v_fmac_f32_e32 v68, v64, v64
	v_fmac_f32_e32 v69, v66, v66
	v_add_f32_e32 v68, v68, v69
	v_add_f32_e32 v68, v72, v68
	ds_swizzle_b32 v69, v68 offset:swizzle(SWAP,16)
	v_cvt_pk_bf16_f32 v64, v64, v65
	v_cvt_pk_bf16_f32 v65, v66, v67
	global_store_dwordx2 v[82:83], v[64:65], off offset:288
	s_waitcnt lgkmcnt(0)
	v_add_f32_e32 v64, v68, v69
	v_mov_b32_e32 v65, v64
	s_nop 1
	v_permlane32_swap_b32_e32 v64, v65
	s_and_saveexec_b64 s[28:29], s[4:5]
	s_cbranch_execz .LBB0_789
	v_add_f32_e32 v66, v64, v65
	v_lshlrev_b64 v[64:65], 6, v[80:81]
	v_lshl_add_u64 v[64:65], s[2:3], 0, v[64:65]
	v_lshl_add_u64 v[64:65], s[26:27], 2, v[64:65]
	s_lshl_b32 s10, s48, 2
	v_lshl_add_u64 v[64:65], v[64:65], 0, s[10:11]
	global_store_dword v[64:65], v66, off
.LBB0_789:
	s_or_b64 exec, exec, s[28:29]
	v_add_u32_e32 v64, 0x80, v142
	v_ashrrev_i32_e32 v65, 31, v64
	v_lshlrev_b64 v[66:67], 11, v[64:65]
	v_lshl_add_u64 v[66:67], s[8:9], 0, v[66:67]
	v_lshl_add_u64 v[66:67], v[140:141], 1, v[66:67]
	s_waitcnt vmcnt(31)
	v_lshlrev_b32_e32 v70, 16, v188
	v_and_b32_e32 v71, 0xffff0000, v188
	v_lshlrev_b32_e32 v68, 16, v189
	v_and_b32_e32 v69, 0xffff0000, v189
	v_pk_add_f32 v[62:63], v[62:63], v[68:69]
	v_pk_add_f32 v[60:61], v[60:61], v[70:71]
	s_nop 0
	v_cvt_pk_bf16_f32 v68, v60, v61
	v_cvt_pk_bf16_f32 v69, v62, v63
	v_mul_f32_e32 v61, v61, v61
	global_store_dwordx2 v[66:67], v[68:69], off
	v_mul_f32_e32 v63, v63, v63
	v_fmac_f32_e32 v61, v60, v60
	v_fmac_f32_e32 v63, v62, v62
	v_add_f32_e32 v60, v61, v63
	s_waitcnt vmcnt(31)
	v_lshlrev_b32_e32 v68, 16, v190
	v_and_b32_e32 v69, 0xffff0000, v190
	v_lshlrev_b32_e32 v70, 16, v191
	v_and_b32_e32 v71, 0xffff0000, v191
	v_pk_add_f32 v[58:59], v[58:59], v[70:71]
	v_pk_add_f32 v[56:57], v[56:57], v[68:69]
	s_nop 0
	v_cvt_pk_bf16_f32 v68, v56, v57
	v_cvt_pk_bf16_f32 v69, v58, v59
	v_mul_f32_e32 v57, v57, v57
	global_store_dwordx2 v[66:67], v[68:69], off offset:32
	v_mul_f32_e32 v59, v59, v59
	v_fmac_f32_e32 v57, v56, v56
	v_fmac_f32_e32 v59, v58, v58
	v_add_f32_e32 v56, v57, v59
	v_add_f32_e32 v56, v60, v56
	s_waitcnt vmcnt(31)
	v_lshlrev_b32_e32 v68, 16, v192
	v_and_b32_e32 v69, 0xffff0000, v192
	v_lshlrev_b32_e32 v70, 16, v193
	v_and_b32_e32 v71, 0xffff0000, v193
	v_pk_add_f32 v[54:55], v[54:55], v[70:71]
	v_pk_add_f32 v[52:53], v[52:53], v[68:69]
	s_nop 0
	v_cvt_pk_bf16_f32 v68, v52, v53
	v_cvt_pk_bf16_f32 v69, v54, v55
	v_mul_f32_e32 v53, v53, v53
	v_mul_f32_e32 v55, v55, v55
	v_fmac_f32_e32 v53, v52, v52
	v_fmac_f32_e32 v55, v54, v54
	v_add_f32_e32 v52, v53, v55
	v_add_f32_e32 v56, v56, v52
	global_store_dwordx2 v[66:67], v[68:69], off offset:256
	s_waitcnt vmcnt(31)
	v_lshlrev_b32_e32 v52, 16, v194
	v_and_b32_e32 v53, 0xffff0000, v194
	v_lshlrev_b32_e32 v54, 16, v195
	v_and_b32_e32 v55, 0xffff0000, v195
	v_pk_add_f32 v[50:51], v[50:51], v[54:55]
	v_pk_add_f32 v[48:49], v[48:49], v[52:53]
	v_mul_f32_e32 v53, v51, v51
	v_mul_f32_e32 v52, v49, v49
	v_fmac_f32_e32 v52, v48, v48
	v_fmac_f32_e32 v53, v50, v50
	v_add_f32_e32 v52, v52, v53
	v_add_f32_e32 v52, v56, v52
	ds_swizzle_b32 v53, v52 offset:swizzle(SWAP,16)
	v_cvt_pk_bf16_f32 v48, v48, v49
	v_cvt_pk_bf16_f32 v49, v50, v51
	global_store_dwordx2 v[66:67], v[48:49], off offset:288
	s_waitcnt lgkmcnt(0)
	v_add_f32_e32 v48, v52, v53
	v_mov_b32_e32 v49, v48
	s_nop 1
	v_permlane32_swap_b32_e32 v48, v49
	s_and_saveexec_b64 s[28:29], s[4:5]
	s_cbranch_execz .LBB0_791
	v_add_f32_e32 v50, v48, v49
	v_lshlrev_b64 v[48:49], 6, v[64:65]
	v_lshl_add_u64 v[48:49], s[2:3], 0, v[48:49]
	v_lshl_add_u64 v[48:49], s[26:27], 2, v[48:49]
	s_lshl_b32 s10, s48, 2
	v_lshl_add_u64 v[48:49], v[48:49], 0, s[10:11]
	global_store_dword v[48:49], v50, off
.LBB0_791:
	s_or_b64 exec, exec, s[28:29]
	v_add_u32_e32 v48, 0x90, v142
	v_ashrrev_i32_e32 v49, 31, v48
	v_lshlrev_b64 v[50:51], 11, v[48:49]
	v_lshl_add_u64 v[50:51], s[8:9], 0, v[50:51]
	v_lshl_add_u64 v[50:51], v[140:141], 1, v[50:51]
	s_waitcnt vmcnt(31)
	v_lshlrev_b32_e32 v54, 16, v196
	v_and_b32_e32 v55, 0xffff0000, v196
	v_lshlrev_b32_e32 v52, 16, v197
	v_and_b32_e32 v53, 0xffff0000, v197
	v_pk_add_f32 v[46:47], v[46:47], v[52:53]
	v_pk_add_f32 v[44:45], v[44:45], v[54:55]
	s_nop 0
	v_cvt_pk_bf16_f32 v52, v44, v45
	v_cvt_pk_bf16_f32 v53, v46, v47
	v_mul_f32_e32 v45, v45, v45
	global_store_dwordx2 v[50:51], v[52:53], off
	v_mul_f32_e32 v47, v47, v47
	v_fmac_f32_e32 v45, v44, v44
	v_fmac_f32_e32 v47, v46, v46
	v_add_f32_e32 v44, v45, v47
	s_waitcnt vmcnt(31)
	v_lshlrev_b32_e32 v52, 16, v198
	v_and_b32_e32 v53, 0xffff0000, v198
	v_lshlrev_b32_e32 v54, 16, v199
	v_and_b32_e32 v55, 0xffff0000, v199
	v_pk_add_f32 v[42:43], v[42:43], v[54:55]
	v_pk_add_f32 v[40:41], v[40:41], v[52:53]
	s_nop 0
	v_cvt_pk_bf16_f32 v52, v40, v41
	v_cvt_pk_bf16_f32 v53, v42, v43
	v_mul_f32_e32 v41, v41, v41
	global_store_dwordx2 v[50:51], v[52:53], off offset:32
	v_mul_f32_e32 v43, v43, v43
	v_fmac_f32_e32 v41, v40, v40
	v_fmac_f32_e32 v43, v42, v42
	v_add_f32_e32 v40, v41, v43
	v_add_f32_e32 v40, v44, v40
	s_waitcnt vmcnt(31)
	v_lshlrev_b32_e32 v52, 16, v200
	v_and_b32_e32 v53, 0xffff0000, v200
	v_lshlrev_b32_e32 v54, 16, v201
	v_and_b32_e32 v55, 0xffff0000, v201
	v_pk_add_f32 v[38:39], v[38:39], v[54:55]
	v_pk_add_f32 v[36:37], v[36:37], v[52:53]
	s_nop 0
	v_cvt_pk_bf16_f32 v52, v36, v37
	v_cvt_pk_bf16_f32 v53, v38, v39
	v_mul_f32_e32 v37, v37, v37
	v_mul_f32_e32 v39, v39, v39
	v_fmac_f32_e32 v37, v36, v36
	v_fmac_f32_e32 v39, v38, v38
	v_add_f32_e32 v36, v37, v39
	v_add_f32_e32 v40, v40, v36
	global_store_dwordx2 v[50:51], v[52:53], off offset:256
	s_waitcnt vmcnt(31)
	v_lshlrev_b32_e32 v36, 16, v202
	v_and_b32_e32 v37, 0xffff0000, v202
	v_lshlrev_b32_e32 v38, 16, v203
	v_and_b32_e32 v39, 0xffff0000, v203
	v_pk_add_f32 v[34:35], v[34:35], v[38:39]
	v_pk_add_f32 v[32:33], v[32:33], v[36:37]
	v_mul_f32_e32 v37, v35, v35
	v_mul_f32_e32 v36, v33, v33
	v_fmac_f32_e32 v36, v32, v32
	v_fmac_f32_e32 v37, v34, v34
	v_add_f32_e32 v36, v36, v37
	v_add_f32_e32 v36, v40, v36
	ds_swizzle_b32 v37, v36 offset:swizzle(SWAP,16)
	v_cvt_pk_bf16_f32 v32, v32, v33
	v_cvt_pk_bf16_f32 v33, v34, v35
	global_store_dwordx2 v[50:51], v[32:33], off offset:288
	s_waitcnt lgkmcnt(0)
	v_add_f32_e32 v32, v36, v37
	v_mov_b32_e32 v33, v32
	s_nop 1
	v_permlane32_swap_b32_e32 v32, v33
	s_and_saveexec_b64 s[28:29], s[4:5]
	s_cbranch_execz .LBB0_793
	v_add_f32_e32 v34, v32, v33
	v_lshlrev_b64 v[32:33], 6, v[48:49]
	v_lshl_add_u64 v[32:33], s[2:3], 0, v[32:33]
	v_lshl_add_u64 v[32:33], s[26:27], 2, v[32:33]
	s_lshl_b32 s10, s48, 2
	v_lshl_add_u64 v[32:33], v[32:33], 0, s[10:11]
	global_store_dword v[32:33], v34, off
.LBB0_793:
	s_or_b64 exec, exec, s[28:29]
	v_add_u32_e32 v32, 0xa0, v142
	v_ashrrev_i32_e32 v33, 31, v32
	v_lshlrev_b64 v[34:35], 11, v[32:33]
	v_lshl_add_u64 v[34:35], s[8:9], 0, v[34:35]
	v_lshl_add_u64 v[34:35], v[140:141], 1, v[34:35]
	s_waitcnt vmcnt(31)
	v_lshlrev_b32_e32 v38, 16, v204
	v_and_b32_e32 v39, 0xffff0000, v204
	v_lshlrev_b32_e32 v36, 16, v205
	v_and_b32_e32 v37, 0xffff0000, v205
	v_pk_add_f32 v[30:31], v[30:31], v[36:37]
	v_pk_add_f32 v[28:29], v[28:29], v[38:39]
	s_nop 0
	v_cvt_pk_bf16_f32 v36, v28, v29
	v_cvt_pk_bf16_f32 v37, v30, v31
	v_mul_f32_e32 v29, v29, v29
	global_store_dwordx2 v[34:35], v[36:37], off
	v_mul_f32_e32 v31, v31, v31
	v_fmac_f32_e32 v29, v28, v28
	v_fmac_f32_e32 v31, v30, v30
	v_add_f32_e32 v28, v29, v31
	s_waitcnt vmcnt(31)
	v_lshlrev_b32_e32 v36, 16, v208
	v_and_b32_e32 v37, 0xffff0000, v208
	v_lshlrev_b32_e32 v38, 16, v209
	v_and_b32_e32 v39, 0xffff0000, v209
	v_pk_add_f32 v[26:27], v[26:27], v[38:39]
	v_pk_add_f32 v[24:25], v[24:25], v[36:37]
	s_nop 0
	v_cvt_pk_bf16_f32 v36, v24, v25
	v_cvt_pk_bf16_f32 v37, v26, v27
	v_mul_f32_e32 v25, v25, v25
	global_store_dwordx2 v[34:35], v[36:37], off offset:32
	v_mul_f32_e32 v27, v27, v27
	v_fmac_f32_e32 v25, v24, v24
	v_fmac_f32_e32 v27, v26, v26
	v_add_f32_e32 v24, v25, v27
	v_add_f32_e32 v24, v28, v24
	s_waitcnt vmcnt(31)
	v_lshlrev_b32_e32 v36, 16, v210
	v_and_b32_e32 v37, 0xffff0000, v210
	v_lshlrev_b32_e32 v38, 16, v211
	v_and_b32_e32 v39, 0xffff0000, v211
	v_pk_add_f32 v[22:23], v[22:23], v[38:39]
	v_pk_add_f32 v[20:21], v[20:21], v[36:37]
	s_nop 0
	v_cvt_pk_bf16_f32 v36, v20, v21
	v_cvt_pk_bf16_f32 v37, v22, v23
	v_mul_f32_e32 v21, v21, v21
	v_mul_f32_e32 v23, v23, v23
	v_fmac_f32_e32 v21, v20, v20
	v_fmac_f32_e32 v23, v22, v22
	v_add_f32_e32 v20, v21, v23
	v_add_f32_e32 v24, v24, v20
	global_store_dwordx2 v[34:35], v[36:37], off offset:256
	s_waitcnt vmcnt(31)
	v_lshlrev_b32_e32 v20, 16, v212
	v_and_b32_e32 v21, 0xffff0000, v212
	v_lshlrev_b32_e32 v22, 16, v213
	v_and_b32_e32 v23, 0xffff0000, v213
	v_pk_add_f32 v[18:19], v[18:19], v[22:23]
	v_pk_add_f32 v[16:17], v[16:17], v[20:21]
	v_mul_f32_e32 v21, v19, v19
	v_mul_f32_e32 v20, v17, v17
	v_fmac_f32_e32 v20, v16, v16
	v_fmac_f32_e32 v21, v18, v18
	v_add_f32_e32 v20, v20, v21
	v_add_f32_e32 v20, v24, v20
	ds_swizzle_b32 v21, v20 offset:swizzle(SWAP,16)
	v_cvt_pk_bf16_f32 v16, v16, v17
	v_cvt_pk_bf16_f32 v17, v18, v19
	global_store_dwordx2 v[34:35], v[16:17], off offset:288
	s_waitcnt lgkmcnt(0)
	v_add_f32_e32 v16, v20, v21
	v_mov_b32_e32 v17, v16
	s_nop 1
	v_permlane32_swap_b32_e32 v16, v17
	s_and_saveexec_b64 s[28:29], s[4:5]
	s_cbranch_execz .LBB0_795
	v_add_f32_e32 v18, v16, v17
	v_lshlrev_b64 v[16:17], 6, v[32:33]
	v_lshl_add_u64 v[16:17], s[2:3], 0, v[16:17]
	v_lshl_add_u64 v[16:17], s[26:27], 2, v[16:17]
	s_lshl_b32 s10, s48, 2
	v_lshl_add_u64 v[16:17], v[16:17], 0, s[10:11]
	global_store_dword v[16:17], v18, off
.LBB0_795:
	s_or_b64 exec, exec, s[28:29]
	v_add_u32_e32 v16, 0xb0, v142
	v_ashrrev_i32_e32 v17, 31, v16
	v_lshlrev_b64 v[18:19], 11, v[16:17]
	v_lshl_add_u64 v[18:19], s[8:9], 0, v[18:19]
	v_lshl_add_u64 v[18:19], v[140:141], 1, v[18:19]
	s_waitcnt vmcnt(31)
	v_lshlrev_b32_e32 v22, 16, v214
	v_and_b32_e32 v23, 0xffff0000, v214
	v_lshlrev_b32_e32 v20, 16, v215
	v_and_b32_e32 v21, 0xffff0000, v215
	v_pk_add_f32 v[14:15], v[14:15], v[20:21]
	v_pk_add_f32 v[12:13], v[12:13], v[22:23]
	s_nop 0
	v_cvt_pk_bf16_f32 v20, v12, v13
	v_cvt_pk_bf16_f32 v21, v14, v15
	v_mul_f32_e32 v13, v13, v13
	global_store_dwordx2 v[18:19], v[20:21], off
	v_mul_f32_e32 v15, v15, v15
	v_fmac_f32_e32 v13, v12, v12
	v_fmac_f32_e32 v15, v14, v14
	v_add_f32_e32 v12, v13, v15
	s_waitcnt vmcnt(31)
	v_lshlrev_b32_e32 v20, 16, v216
	v_and_b32_e32 v21, 0xffff0000, v216
	v_lshlrev_b32_e32 v22, 16, v217
	v_and_b32_e32 v23, 0xffff0000, v217
	v_pk_add_f32 v[10:11], v[10:11], v[22:23]
	v_pk_add_f32 v[8:9], v[8:9], v[20:21]
	s_nop 0
	v_cvt_pk_bf16_f32 v20, v8, v9
	v_cvt_pk_bf16_f32 v21, v10, v11
	v_mul_f32_e32 v9, v9, v9
	global_store_dwordx2 v[18:19], v[20:21], off offset:32
	v_mul_f32_e32 v11, v11, v11
	v_fmac_f32_e32 v9, v8, v8
	v_fmac_f32_e32 v11, v10, v10
	v_add_f32_e32 v8, v9, v11
	v_add_f32_e32 v8, v12, v8
	s_waitcnt vmcnt(31)
	v_lshlrev_b32_e32 v20, 16, v218
	v_and_b32_e32 v21, 0xffff0000, v218
	v_lshlrev_b32_e32 v22, 16, v219
	v_and_b32_e32 v23, 0xffff0000, v219
	v_pk_add_f32 v[6:7], v[6:7], v[22:23]
	v_pk_add_f32 v[4:5], v[4:5], v[20:21]
	s_nop 0
	v_cvt_pk_bf16_f32 v20, v4, v5
	v_cvt_pk_bf16_f32 v21, v6, v7
	v_mul_f32_e32 v5, v5, v5
	v_mul_f32_e32 v7, v7, v7
	v_fmac_f32_e32 v5, v4, v4
	v_fmac_f32_e32 v7, v6, v6
	v_add_f32_e32 v4, v5, v7
	v_add_f32_e32 v8, v8, v4
	global_store_dwordx2 v[18:19], v[20:21], off offset:256
	s_waitcnt vmcnt(31)
	v_lshlrev_b32_e32 v4, 16, v220
	v_and_b32_e32 v5, 0xffff0000, v220
	v_lshlrev_b32_e32 v6, 16, v221
	v_and_b32_e32 v7, 0xffff0000, v221
	v_pk_add_f32 v[2:3], v[2:3], v[6:7]
	v_pk_add_f32 v[0:1], v[0:1], v[4:5]
	v_mul_f32_e32 v5, v3, v3
	v_mul_f32_e32 v4, v1, v1
	v_fmac_f32_e32 v4, v0, v0
	v_fmac_f32_e32 v5, v2, v2
	v_add_f32_e32 v4, v4, v5
	v_add_f32_e32 v4, v8, v4
	ds_swizzle_b32 v5, v4 offset:swizzle(SWAP,16)
	v_cvt_pk_bf16_f32 v0, v0, v1
	v_cvt_pk_bf16_f32 v1, v2, v3
	global_store_dwordx2 v[18:19], v[0:1], off offset:288
	s_waitcnt lgkmcnt(0)
	v_add_f32_e32 v0, v4, v5
	v_mov_b32_e32 v1, v0
	s_nop 1
	v_permlane32_swap_b32_e32 v0, v1
	s_and_saveexec_b64 s[28:29], s[4:5]
	s_cbranch_execz .LBB0_797
	v_add_f32_e32 v2, v0, v1
	v_lshlrev_b64 v[0:1], 6, v[16:17]
	v_lshl_add_u64 v[0:1], s[2:3], 0, v[0:1]
	v_lshl_add_u64 v[0:1], s[26:27], 2, v[0:1]
	s_lshl_b32 s10, s48, 2
	v_lshl_add_u64 v[0:1], v[0:1], 0, s[10:11]
	global_store_dword v[0:1], v2, off

.LBB0_1275:
	v_lshl_add_u32 v142, s26, 8, v144
	v_ashrrev_i32_e32 v143, 31, v142
	v_lshl_or_b32 v140, s2, 8, v146
	v_lshlrev_b64 v[150:151], 11, v[142:143]
	v_ashrrev_i32_e32 v141, 31, v140
	v_lshl_add_u64 v[150:151], s[8:9], 0, v[150:151]
	v_lshl_add_u64 v[150:151], v[140:141], 1, v[150:151]
	s_mov_b64 s[98:99], 0x8000
	s_mov_b64 s[100:101], 0x28000
	global_load_dwordx2 v[156:157], v[150:151], off
	global_load_dwordx2 v[158:159], v[150:151], off offset:32
	global_load_dwordx2 v[160:161], v[150:151], off offset:256
	global_load_dwordx2 v[162:163], v[150:151], off offset:288
	v_lshl_add_u64 v[222:223], v[150:151], 0, s[98:99]
	global_load_dwordx2 v[164:165], v[222:223], off
	global_load_dwordx2 v[166:167], v[222:223], off offset:32
	global_load_dwordx2 v[168:169], v[222:223], off offset:256
	global_load_dwordx2 v[170:171], v[222:223], off offset:288
	v_lshl_add_u64 v[222:223], v[222:223], 0, s[98:99]
	global_load_dwordx2 v[172:173], v[222:223], off
	global_load_dwordx2 v[174:175], v[222:223], off offset:32
	global_load_dwordx2 v[176:177], v[222:223], off offset:256
	global_load_dwordx2 v[178:179], v[222:223], off offset:288
	v_lshl_add_u64 v[222:223], v[222:223], 0, s[98:99]
	global_load_dwordx2 v[180:181], v[222:223], off
	global_load_dwordx2 v[182:183], v[222:223], off offset:32
	global_load_dwordx2 v[184:185], v[222:223], off offset:256
	global_load_dwordx2 v[186:187], v[222:223], off offset:288
	v_lshl_add_u64 v[222:223], v[222:223], 0, s[100:101]
	global_load_dwordx2 v[188:189], v[222:223], off
	global_load_dwordx2 v[190:191], v[222:223], off offset:32
	global_load_dwordx2 v[192:193], v[222:223], off offset:256
	global_load_dwordx2 v[194:195], v[222:223], off offset:288
	v_lshl_add_u64 v[222:223], v[222:223], 0, s[98:99]
	global_load_dwordx2 v[196:197], v[222:223], off
	global_load_dwordx2 v[198:199], v[222:223], off offset:32
	global_load_dwordx2 v[200:201], v[222:223], off offset:256
	global_load_dwordx2 v[202:203], v[222:223], off offset:288
	v_lshl_add_u64 v[222:223], v[222:223], 0, s[98:99]
	global_load_dwordx2 v[204:205], v[222:223], off
	global_load_dwordx2 v[208:209], v[222:223], off offset:32
	global_load_dwordx2 v[210:211], v[222:223], off offset:256
	global_load_dwordx2 v[212:213], v[222:223], off offset:288
	v_lshl_add_u64 v[222:223], v[222:223], 0, s[98:99]
	global_load_dwordx2 v[214:215], v[222:223], off
	global_load_dwordx2 v[216:217], v[222:223], off offset:32
	global_load_dwordx2 v[218:219], v[222:223], off offset:256
	global_load_dwordx2 v[220:221], v[222:223], off offset:288
	s_lshl_b32 s26, s2, 2
	s_ashr_i32 s27, s26, 31
	s_waitcnt vmcnt(31)
	v_lshlrev_b32_e32 v154, 16, v156
	v_and_b32_e32 v155, 0xffff0000, v156
	v_lshlrev_b32_e32 v152, 16, v157
	v_and_b32_e32 v153, 0xffff0000, v157
	v_pk_add_f32 v[126:127], v[126:127], v[152:153]
	v_pk_add_f32 v[124:125], v[124:125], v[154:155]
	s_nop 0
	v_cvt_pk_bf16_f32 v152, v124, v125
	v_cvt_pk_bf16_f32 v153, v126, v127
	v_mul_f32_e32 v125, v125, v125
	global_store_dwordx2 v[150:151], v[152:153], off
	v_mul_f32_e32 v127, v127, v127
	v_fmac_f32_e32 v125, v124, v124
	v_fmac_f32_e32 v127, v126, v126
	v_add_f32_e32 v124, v125, v127
	s_waitcnt vmcnt(31)
	v_lshlrev_b32_e32 v152, 16, v158
	v_and_b32_e32 v153, 0xffff0000, v158
	v_lshlrev_b32_e32 v154, 16, v159
	v_and_b32_e32 v155, 0xffff0000, v159
	v_pk_add_f32 v[122:123], v[122:123], v[154:155]
	v_pk_add_f32 v[120:121], v[120:121], v[152:153]
	s_nop 0
	v_cvt_pk_bf16_f32 v152, v120, v121
	v_cvt_pk_bf16_f32 v153, v122, v123
	v_mul_f32_e32 v121, v121, v121
	global_store_dwordx2 v[150:151], v[152:153], off offset:32
	v_mul_f32_e32 v123, v123, v123
	v_fmac_f32_e32 v121, v120, v120
	v_fmac_f32_e32 v123, v122, v122
	v_add_f32_e32 v120, v121, v123
	v_add_f32_e32 v120, v124, v120
	s_waitcnt vmcnt(31)
	v_lshlrev_b32_e32 v152, 16, v160
	v_and_b32_e32 v153, 0xffff0000, v160
	v_lshlrev_b32_e32 v154, 16, v161
	v_and_b32_e32 v155, 0xffff0000, v161
	v_pk_add_f32 v[118:119], v[118:119], v[154:155]
	v_pk_add_f32 v[116:117], v[116:117], v[152:153]
	s_nop 0
	v_cvt_pk_bf16_f32 v152, v116, v117
	v_cvt_pk_bf16_f32 v153, v118, v119
	v_mul_f32_e32 v117, v117, v117
	v_mul_f32_e32 v119, v119, v119
	v_fmac_f32_e32 v117, v116, v116
	v_fmac_f32_e32 v119, v118, v118
	v_add_f32_e32 v116, v117, v119
	v_add_f32_e32 v120, v120, v116
	global_store_dwordx2 v[150:151], v[152:153], off offset:256
	s_waitcnt vmcnt(31)
	v_lshlrev_b32_e32 v116, 16, v162
	v_and_b32_e32 v117, 0xffff0000, v162
	v_lshlrev_b32_e32 v118, 16, v163
	v_and_b32_e32 v119, 0xffff0000, v163
	v_pk_add_f32 v[114:115], v[114:115], v[118:119]
	v_pk_add_f32 v[112:113], v[112:113], v[116:117]
	v_mul_f32_e32 v117, v115, v115
	v_mul_f32_e32 v116, v113, v113
	v_fmac_f32_e32 v116, v112, v112
	v_fmac_f32_e32 v117, v114, v114
	v_add_f32_e32 v116, v116, v117
	v_add_f32_e32 v116, v120, v116
	ds_swizzle_b32 v117, v116 offset:swizzle(SWAP,16)
	v_cvt_pk_bf16_f32 v112, v112, v113
	v_cvt_pk_bf16_f32 v113, v114, v115
	global_store_dwordx2 v[150:151], v[112:113], off offset:288
	s_waitcnt lgkmcnt(0)
	v_add_f32_e32 v112, v116, v117
	v_mov_b32_e32 v113, v112
	s_nop 1
	v_permlane32_swap_b32_e32 v112, v113
	s_and_saveexec_b64 s[28:29], s[4:5]
	s_cbranch_execz .LBB0_1277
	v_add_f32_e32 v114, v112, v113
	v_lshlrev_b64 v[112:113], 6, v[142:143]
	v_lshl_add_u64 v[112:113], s[10:11], 0, v[112:113]
	v_lshl_add_u64 v[112:113], s[26:27], 2, v[112:113]
	s_lshl_b32 s2, s48, 2
	v_lshl_add_u64 v[112:113], v[112:113], 0, s[2:3]
	global_store_dword v[112:113], v114, off
.LBB0_1277:
	s_or_b64 exec, exec, s[28:29]
	v_or_b32_e32 v112, 16, v142
	v_ashrrev_i32_e32 v113, 31, v112
	v_lshlrev_b64 v[114:115], 11, v[112:113]
	v_lshl_add_u64 v[114:115], s[8:9], 0, v[114:115]
	v_lshl_add_u64 v[114:115], v[140:141], 1, v[114:115]
	s_waitcnt vmcnt(31)
	v_lshlrev_b32_e32 v118, 16, v164
	v_and_b32_e32 v119, 0xffff0000, v164
	v_lshlrev_b32_e32 v116, 16, v165
	v_and_b32_e32 v117, 0xffff0000, v165
	v_pk_add_f32 v[110:111], v[110:111], v[116:117]
	v_pk_add_f32 v[108:109], v[108:109], v[118:119]
	s_nop 0
	v_cvt_pk_bf16_f32 v116, v108, v109
	v_cvt_pk_bf16_f32 v117, v110, v111
	v_mul_f32_e32 v109, v109, v109
	global_store_dwordx2 v[114:115], v[116:117], off
	v_mul_f32_e32 v111, v111, v111
	v_fmac_f32_e32 v109, v108, v108
	v_fmac_f32_e32 v111, v110, v110
	v_add_f32_e32 v108, v109, v111
	s_waitcnt vmcnt(31)
	v_lshlrev_b32_e32 v116, 16, v166
	v_and_b32_e32 v117, 0xffff0000, v166
	v_lshlrev_b32_e32 v118, 16, v167
	v_and_b32_e32 v119, 0xffff0000, v167
	v_pk_add_f32 v[106:107], v[106:107], v[118:119]
	v_pk_add_f32 v[104:105], v[104:105], v[116:117]
	s_nop 0
	v_cvt_pk_bf16_f32 v116, v104, v105
	v_cvt_pk_bf16_f32 v117, v106, v107
	v_mul_f32_e32 v105, v105, v105
	global_store_dwordx2 v[114:115], v[116:117], off offset:32
	v_mul_f32_e32 v107, v107, v107
	v_fmac_f32_e32 v105, v104, v104
	v_fmac_f32_e32 v107, v106, v106
	v_add_f32_e32 v104, v105, v107
	v_add_f32_e32 v104, v108, v104
	s_waitcnt vmcnt(31)
	v_lshlrev_b32_e32 v116, 16, v168
	v_and_b32_e32 v117, 0xffff0000, v168
	v_lshlrev_b32_e32 v118, 16, v169
	v_and_b32_e32 v119, 0xffff0000, v169
	v_pk_add_f32 v[102:103], v[102:103], v[118:119]
	v_pk_add_f32 v[100:101], v[100:101], v[116:117]
	s_nop 0
	v_cvt_pk_bf16_f32 v116, v100, v101
	v_cvt_pk_bf16_f32 v117, v102, v103
	v_mul_f32_e32 v101, v101, v101
	v_mul_f32_e32 v103, v103, v103
	v_fmac_f32_e32 v101, v100, v100
	v_fmac_f32_e32 v103, v102, v102
	v_add_f32_e32 v100, v101, v103
	v_add_f32_e32 v104, v104, v100
	global_store_dwordx2 v[114:115], v[116:117], off offset:256
	s_waitcnt vmcnt(31)
	v_lshlrev_b32_e32 v100, 16, v170
	v_and_b32_e32 v101, 0xffff0000, v170
	v_lshlrev_b32_e32 v102, 16, v171
	v_and_b32_e32 v103, 0xffff0000, v171
	v_pk_add_f32 v[98:99], v[98:99], v[102:103]
	v_pk_add_f32 v[96:97], v[96:97], v[100:101]
	v_mul_f32_e32 v101, v99, v99
	v_mul_f32_e32 v100, v97, v97
	v_fmac_f32_e32 v100, v96, v96
	v_fmac_f32_e32 v101, v98, v98
	v_add_f32_e32 v100, v100, v101
	v_add_f32_e32 v100, v104, v100
	ds_swizzle_b32 v101, v100 offset:swizzle(SWAP,16)
	v_cvt_pk_bf16_f32 v96, v96, v97
	v_cvt_pk_bf16_f32 v97, v98, v99
	global_store_dwordx2 v[114:115], v[96:97], off offset:288
	s_waitcnt lgkmcnt(0)
	v_add_f32_e32 v96, v100, v101
	v_mov_b32_e32 v97, v96
	s_nop 1
	v_permlane32_swap_b32_e32 v96, v97
	s_and_saveexec_b64 s[28:29], s[4:5]
	s_cbranch_execz .LBB0_1279
	v_add_f32_e32 v98, v96, v97
	v_lshlrev_b64 v[96:97], 6, v[112:113]
	v_lshl_add_u64 v[96:97], s[10:11], 0, v[96:97]
	v_lshl_add_u64 v[96:97], s[26:27], 2, v[96:97]
	s_lshl_b32 s2, s48, 2
	v_lshl_add_u64 v[96:97], v[96:97], 0, s[2:3]
	global_store_dword v[96:97], v98, off
.LBB0_1279:
	s_or_b64 exec, exec, s[28:29]
	v_or_b32_e32 v96, 32, v142
	v_ashrrev_i32_e32 v97, 31, v96
	v_lshlrev_b64 v[98:99], 11, v[96:97]
	v_lshl_add_u64 v[98:99], s[8:9], 0, v[98:99]
	v_lshl_add_u64 v[98:99], v[140:141], 1, v[98:99]
	s_waitcnt vmcnt(31)
	v_lshlrev_b32_e32 v102, 16, v172
	v_and_b32_e32 v103, 0xffff0000, v172
	v_lshlrev_b32_e32 v100, 16, v173
	v_and_b32_e32 v101, 0xffff0000, v173
	v_pk_add_f32 v[94:95], v[94:95], v[100:101]
	v_pk_add_f32 v[92:93], v[92:93], v[102:103]
	s_nop 0
	v_cvt_pk_bf16_f32 v100, v92, v93
	v_cvt_pk_bf16_f32 v101, v94, v95
	v_mul_f32_e32 v93, v93, v93
	global_store_dwordx2 v[98:99], v[100:101], off
	v_mul_f32_e32 v95, v95, v95
	v_fmac_f32_e32 v93, v92, v92
	v_fmac_f32_e32 v95, v94, v94
	v_add_f32_e32 v92, v93, v95
	s_waitcnt vmcnt(31)
	v_lshlrev_b32_e32 v100, 16, v174
	v_and_b32_e32 v101, 0xffff0000, v174
	v_lshlrev_b32_e32 v102, 16, v175
	v_and_b32_e32 v103, 0xffff0000, v175
	v_pk_add_f32 v[90:91], v[90:91], v[102:103]
	v_pk_add_f32 v[88:89], v[88:89], v[100:101]
	s_nop 0
	v_cvt_pk_bf16_f32 v100, v88, v89
	v_cvt_pk_bf16_f32 v101, v90, v91
	v_mul_f32_e32 v89, v89, v89
	global_store_dwordx2 v[98:99], v[100:101], off offset:32
	v_mul_f32_e32 v91, v91, v91
	v_fmac_f32_e32 v89, v88, v88
	v_fmac_f32_e32 v91, v90, v90
	v_add_f32_e32 v88, v89, v91
	v_add_f32_e32 v88, v92, v88
	s_waitcnt vmcnt(31)
	v_lshlrev_b32_e32 v100, 16, v176
	v_and_b32_e32 v101, 0xffff0000, v176
	v_lshlrev_b32_e32 v102, 16, v177
	v_and_b32_e32 v103, 0xffff0000, v177
	v_pk_add_f32 v[86:87], v[86:87], v[102:103]
	v_pk_add_f32 v[84:85], v[84:85], v[100:101]
	s_nop 0
	v_cvt_pk_bf16_f32 v100, v84, v85
	v_cvt_pk_bf16_f32 v101, v86, v87
	v_mul_f32_e32 v85, v85, v85
	v_mul_f32_e32 v87, v87, v87
	v_fmac_f32_e32 v85, v84, v84
	v_fmac_f32_e32 v87, v86, v86
	v_add_f32_e32 v84, v85, v87
	v_add_f32_e32 v88, v88, v84
	global_store_dwordx2 v[98:99], v[100:101], off offset:256
	s_waitcnt vmcnt(31)
	v_lshlrev_b32_e32 v84, 16, v178
	v_and_b32_e32 v85, 0xffff0000, v178
	v_lshlrev_b32_e32 v86, 16, v179
	v_and_b32_e32 v87, 0xffff0000, v179
	v_pk_add_f32 v[82:83], v[82:83], v[86:87]
	v_pk_add_f32 v[80:81], v[80:81], v[84:85]
	v_mul_f32_e32 v85, v83, v83
	v_mul_f32_e32 v84, v81, v81
	v_fmac_f32_e32 v84, v80, v80
	v_fmac_f32_e32 v85, v82, v82
	v_add_f32_e32 v84, v84, v85
	v_add_f32_e32 v84, v88, v84
	ds_swizzle_b32 v85, v84 offset:swizzle(SWAP,16)
	v_cvt_pk_bf16_f32 v80, v80, v81
	v_cvt_pk_bf16_f32 v81, v82, v83
	global_store_dwordx2 v[98:99], v[80:81], off offset:288
	s_waitcnt lgkmcnt(0)
	v_add_f32_e32 v80, v84, v85
	v_mov_b32_e32 v81, v80
	s_nop 1
	v_permlane32_swap_b32_e32 v80, v81
	s_and_saveexec_b64 s[28:29], s[4:5]
	s_cbranch_execz .LBB0_1281
	v_add_f32_e32 v82, v80, v81
	v_lshlrev_b64 v[80:81], 6, v[96:97]
	v_lshl_add_u64 v[80:81], s[10:11], 0, v[80:81]
	v_lshl_add_u64 v[80:81], s[26:27], 2, v[80:81]
	s_lshl_b32 s2, s48, 2
	v_lshl_add_u64 v[80:81], v[80:81], 0, s[2:3]
	global_store_dword v[80:81], v82, off
.LBB0_1281:
	s_or_b64 exec, exec, s[28:29]
	v_or_b32_e32 v80, 48, v142
	v_ashrrev_i32_e32 v81, 31, v80
	v_lshlrev_b64 v[82:83], 11, v[80:81]
	v_lshl_add_u64 v[82:83], s[8:9], 0, v[82:83]
	v_lshl_add_u64 v[82:83], v[140:141], 1, v[82:83]
	s_waitcnt vmcnt(31)
	v_lshlrev_b32_e32 v86, 16, v180
	v_and_b32_e32 v87, 0xffff0000, v180
	v_lshlrev_b32_e32 v84, 16, v181
	v_and_b32_e32 v85, 0xffff0000, v181
	v_pk_add_f32 v[78:79], v[78:79], v[84:85]
	v_pk_add_f32 v[76:77], v[76:77], v[86:87]
	s_nop 0
	v_cvt_pk_bf16_f32 v84, v76, v77
	v_cvt_pk_bf16_f32 v85, v78, v79
	v_mul_f32_e32 v77, v77, v77
	global_store_dwordx2 v[82:83], v[84:85], off
	v_mul_f32_e32 v79, v79, v79
	v_fmac_f32_e32 v77, v76, v76
	v_fmac_f32_e32 v79, v78, v78
	v_add_f32_e32 v76, v77, v79
	s_waitcnt vmcnt(31)
	v_lshlrev_b32_e32 v84, 16, v182
	v_and_b32_e32 v85, 0xffff0000, v182
	v_lshlrev_b32_e32 v86, 16, v183
	v_and_b32_e32 v87, 0xffff0000, v183
	v_pk_add_f32 v[74:75], v[74:75], v[86:87]
	v_pk_add_f32 v[72:73], v[72:73], v[84:85]
	s_nop 0
	v_cvt_pk_bf16_f32 v84, v72, v73
	v_cvt_pk_bf16_f32 v85, v74, v75
	v_mul_f32_e32 v73, v73, v73
	global_store_dwordx2 v[82:83], v[84:85], off offset:32
	v_mul_f32_e32 v75, v75, v75
	v_fmac_f32_e32 v73, v72, v72
	v_fmac_f32_e32 v75, v74, v74
	v_add_f32_e32 v72, v73, v75
	v_add_f32_e32 v72, v76, v72
	s_waitcnt vmcnt(31)
	v_lshlrev_b32_e32 v84, 16, v184
	v_and_b32_e32 v85, 0xffff0000, v184
	v_lshlrev_b32_e32 v86, 16, v185
	v_and_b32_e32 v87, 0xffff0000, v185
	v_pk_add_f32 v[70:71], v[70:71], v[86:87]
	v_pk_add_f32 v[68:69], v[68:69], v[84:85]
	s_nop 0
	v_cvt_pk_bf16_f32 v84, v68, v69
	v_cvt_pk_bf16_f32 v85, v70, v71
	v_mul_f32_e32 v69, v69, v69
	v_mul_f32_e32 v71, v71, v71
	v_fmac_f32_e32 v69, v68, v68
	v_fmac_f32_e32 v71, v70, v70
	v_add_f32_e32 v68, v69, v71
	v_add_f32_e32 v72, v72, v68
	global_store_dwordx2 v[82:83], v[84:85], off offset:256
	s_waitcnt vmcnt(31)
	v_lshlrev_b32_e32 v68, 16, v186
	v_and_b32_e32 v69, 0xffff0000, v186
	v_lshlrev_b32_e32 v70, 16, v187
	v_and_b32_e32 v71, 0xffff0000, v187
	v_pk_add_f32 v[66:67], v[66:67], v[70:71]
	v_pk_add_f32 v[64:65], v[64:65], v[68:69]
	v_mul_f32_e32 v69, v67, v67
	v_mul_f32_e32 v68, v65, v65
	v_fmac_f32_e32 v68, v64, v64
	v_fmac_f32_e32 v69, v66, v66
	v_add_f32_e32 v68, v68, v69
	v_add_f32_e32 v68, v72, v68
	ds_swizzle_b32 v69, v68 offset:swizzle(SWAP,16)
	v_cvt_pk_bf16_f32 v64, v64, v65
	v_cvt_pk_bf16_f32 v65, v66, v67
	global_store_dwordx2 v[82:83], v[64:65], off offset:288
	s_waitcnt lgkmcnt(0)
	v_add_f32_e32 v64, v68, v69
	v_mov_b32_e32 v65, v64
	s_nop 1
	v_permlane32_swap_b32_e32 v64, v65
	s_and_saveexec_b64 s[28:29], s[4:5]
	s_cbranch_execz .LBB0_1283
	v_add_f32_e32 v66, v64, v65
	v_lshlrev_b64 v[64:65], 6, v[80:81]
	v_lshl_add_u64 v[64:65], s[10:11], 0, v[64:65]
	v_lshl_add_u64 v[64:65], s[26:27], 2, v[64:65]
	s_lshl_b32 s2, s48, 2
	v_lshl_add_u64 v[64:65], v[64:65], 0, s[2:3]
	global_store_dword v[64:65], v66, off
.LBB0_1283:
	s_or_b64 exec, exec, s[28:29]
	v_add_u32_e32 v64, 0x80, v142
	v_ashrrev_i32_e32 v65, 31, v64
	v_lshlrev_b64 v[66:67], 11, v[64:65]
	v_lshl_add_u64 v[66:67], s[8:9], 0, v[66:67]
	v_lshl_add_u64 v[66:67], v[140:141], 1, v[66:67]
	s_waitcnt vmcnt(31)
	v_lshlrev_b32_e32 v70, 16, v188
	v_and_b32_e32 v71, 0xffff0000, v188
	v_lshlrev_b32_e32 v68, 16, v189
	v_and_b32_e32 v69, 0xffff0000, v189
	v_pk_add_f32 v[62:63], v[62:63], v[68:69]
	v_pk_add_f32 v[60:61], v[60:61], v[70:71]
	s_nop 0
	v_cvt_pk_bf16_f32 v68, v60, v61
	v_cvt_pk_bf16_f32 v69, v62, v63
	v_mul_f32_e32 v61, v61, v61
	global_store_dwordx2 v[66:67], v[68:69], off
	v_mul_f32_e32 v63, v63, v63
	v_fmac_f32_e32 v61, v60, v60
	v_fmac_f32_e32 v63, v62, v62
	v_add_f32_e32 v60, v61, v63
	s_waitcnt vmcnt(31)
	v_lshlrev_b32_e32 v68, 16, v190
	v_and_b32_e32 v69, 0xffff0000, v190
	v_lshlrev_b32_e32 v70, 16, v191
	v_and_b32_e32 v71, 0xffff0000, v191
	v_pk_add_f32 v[58:59], v[58:59], v[70:71]
	v_pk_add_f32 v[56:57], v[56:57], v[68:69]
	s_nop 0
	v_cvt_pk_bf16_f32 v68, v56, v57
	v_cvt_pk_bf16_f32 v69, v58, v59
	v_mul_f32_e32 v57, v57, v57
	global_store_dwordx2 v[66:67], v[68:69], off offset:32
	v_mul_f32_e32 v59, v59, v59
	v_fmac_f32_e32 v57, v56, v56
	v_fmac_f32_e32 v59, v58, v58
	v_add_f32_e32 v56, v57, v59
	v_add_f32_e32 v56, v60, v56
	s_waitcnt vmcnt(31)
	v_lshlrev_b32_e32 v68, 16, v192
	v_and_b32_e32 v69, 0xffff0000, v192
	v_lshlrev_b32_e32 v70, 16, v193
	v_and_b32_e32 v71, 0xffff0000, v193
	v_pk_add_f32 v[54:55], v[54:55], v[70:71]
	v_pk_add_f32 v[52:53], v[52:53], v[68:69]
	s_nop 0
	v_cvt_pk_bf16_f32 v68, v52, v53
	v_cvt_pk_bf16_f32 v69, v54, v55
	v_mul_f32_e32 v53, v53, v53
	v_mul_f32_e32 v55, v55, v55
	v_fmac_f32_e32 v53, v52, v52
	v_fmac_f32_e32 v55, v54, v54
	v_add_f32_e32 v52, v53, v55
	v_add_f32_e32 v56, v56, v52
	global_store_dwordx2 v[66:67], v[68:69], off offset:256
	s_waitcnt vmcnt(31)
	v_lshlrev_b32_e32 v52, 16, v194
	v_and_b32_e32 v53, 0xffff0000, v194
	v_lshlrev_b32_e32 v54, 16, v195
	v_and_b32_e32 v55, 0xffff0000, v195
	v_pk_add_f32 v[50:51], v[50:51], v[54:55]
	v_pk_add_f32 v[48:49], v[48:49], v[52:53]
	v_mul_f32_e32 v53, v51, v51
	v_mul_f32_e32 v52, v49, v49
	v_fmac_f32_e32 v52, v48, v48
	v_fmac_f32_e32 v53, v50, v50
	v_add_f32_e32 v52, v52, v53
	v_add_f32_e32 v52, v56, v52
	ds_swizzle_b32 v53, v52 offset:swizzle(SWAP,16)
	v_cvt_pk_bf16_f32 v48, v48, v49
	v_cvt_pk_bf16_f32 v49, v50, v51
	global_store_dwordx2 v[66:67], v[48:49], off offset:288
	s_waitcnt lgkmcnt(0)
	v_add_f32_e32 v48, v52, v53
	v_mov_b32_e32 v49, v48
	s_nop 1
	v_permlane32_swap_b32_e32 v48, v49
	s_and_saveexec_b64 s[28:29], s[4:5]
	s_cbranch_execz .LBB0_1285
	v_add_f32_e32 v50, v48, v49
	v_lshlrev_b64 v[48:49], 6, v[64:65]
	v_lshl_add_u64 v[48:49], s[10:11], 0, v[48:49]
	v_lshl_add_u64 v[48:49], s[26:27], 2, v[48:49]
	s_lshl_b32 s2, s48, 2
	v_lshl_add_u64 v[48:49], v[48:49], 0, s[2:3]
	global_store_dword v[48:49], v50, off
.LBB0_1285:
	s_or_b64 exec, exec, s[28:29]
	v_add_u32_e32 v48, 0x90, v142
	v_ashrrev_i32_e32 v49, 31, v48
	v_lshlrev_b64 v[50:51], 11, v[48:49]
	v_lshl_add_u64 v[50:51], s[8:9], 0, v[50:51]
	v_lshl_add_u64 v[50:51], v[140:141], 1, v[50:51]
	s_waitcnt vmcnt(31)
	v_lshlrev_b32_e32 v54, 16, v196
	v_and_b32_e32 v55, 0xffff0000, v196
	v_lshlrev_b32_e32 v52, 16, v197
	v_and_b32_e32 v53, 0xffff0000, v197
	v_pk_add_f32 v[46:47], v[46:47], v[52:53]
	v_pk_add_f32 v[44:45], v[44:45], v[54:55]
	s_nop 0
	v_cvt_pk_bf16_f32 v52, v44, v45
	v_cvt_pk_bf16_f32 v53, v46, v47
	v_mul_f32_e32 v45, v45, v45
	global_store_dwordx2 v[50:51], v[52:53], off
	v_mul_f32_e32 v47, v47, v47
	v_fmac_f32_e32 v45, v44, v44
	v_fmac_f32_e32 v47, v46, v46
	v_add_f32_e32 v44, v45, v47
	s_waitcnt vmcnt(31)
	v_lshlrev_b32_e32 v52, 16, v198
	v_and_b32_e32 v53, 0xffff0000, v198
	v_lshlrev_b32_e32 v54, 16, v199
	v_and_b32_e32 v55, 0xffff0000, v199
	v_pk_add_f32 v[42:43], v[42:43], v[54:55]
	v_pk_add_f32 v[40:41], v[40:41], v[52:53]
	s_nop 0
	v_cvt_pk_bf16_f32 v52, v40, v41
	v_cvt_pk_bf16_f32 v53, v42, v43
	v_mul_f32_e32 v41, v41, v41
	global_store_dwordx2 v[50:51], v[52:53], off offset:32
	v_mul_f32_e32 v43, v43, v43
	v_fmac_f32_e32 v41, v40, v40
	v_fmac_f32_e32 v43, v42, v42
	v_add_f32_e32 v40, v41, v43
	v_add_f32_e32 v40, v44, v40
	s_waitcnt vmcnt(31)
	v_lshlrev_b32_e32 v52, 16, v200
	v_and_b32_e32 v53, 0xffff0000, v200
	v_lshlrev_b32_e32 v54, 16, v201
	v_and_b32_e32 v55, 0xffff0000, v201
	v_pk_add_f32 v[38:39], v[38:39], v[54:55]
	v_pk_add_f32 v[36:37], v[36:37], v[52:53]
	s_nop 0
	v_cvt_pk_bf16_f32 v52, v36, v37
	v_cvt_pk_bf16_f32 v53, v38, v39
	v_mul_f32_e32 v37, v37, v37
	v_mul_f32_e32 v39, v39, v39
	v_fmac_f32_e32 v37, v36, v36
	v_fmac_f32_e32 v39, v38, v38
	v_add_f32_e32 v36, v37, v39
	v_add_f32_e32 v40, v40, v36
	global_store_dwordx2 v[50:51], v[52:53], off offset:256
	s_waitcnt vmcnt(31)
	v_lshlrev_b32_e32 v36, 16, v202
	v_and_b32_e32 v37, 0xffff0000, v202
	v_lshlrev_b32_e32 v38, 16, v203
	v_and_b32_e32 v39, 0xffff0000, v203
	v_pk_add_f32 v[34:35], v[34:35], v[38:39]
	v_pk_add_f32 v[32:33], v[32:33], v[36:37]
	v_mul_f32_e32 v37, v35, v35
	v_mul_f32_e32 v36, v33, v33
	v_fmac_f32_e32 v36, v32, v32
	v_fmac_f32_e32 v37, v34, v34
	v_add_f32_e32 v36, v36, v37
	v_add_f32_e32 v36, v40, v36
	ds_swizzle_b32 v37, v36 offset:swizzle(SWAP,16)
	v_cvt_pk_bf16_f32 v32, v32, v33
	v_cvt_pk_bf16_f32 v33, v34, v35
	global_store_dwordx2 v[50:51], v[32:33], off offset:288
	s_waitcnt lgkmcnt(0)
	v_add_f32_e32 v32, v36, v37
	v_mov_b32_e32 v33, v32
	s_nop 1
	v_permlane32_swap_b32_e32 v32, v33
	s_and_saveexec_b64 s[28:29], s[4:5]
	s_cbranch_execz .LBB0_1287
	v_add_f32_e32 v34, v32, v33
	v_lshlrev_b64 v[32:33], 6, v[48:49]
	v_lshl_add_u64 v[32:33], s[10:11], 0, v[32:33]
	v_lshl_add_u64 v[32:33], s[26:27], 2, v[32:33]
	s_lshl_b32 s2, s48, 2
	v_lshl_add_u64 v[32:33], v[32:33], 0, s[2:3]
	global_store_dword v[32:33], v34, off
.LBB0_1287:
	s_or_b64 exec, exec, s[28:29]
	v_add_u32_e32 v32, 0xa0, v142
	v_ashrrev_i32_e32 v33, 31, v32
	v_lshlrev_b64 v[34:35], 11, v[32:33]
	v_lshl_add_u64 v[34:35], s[8:9], 0, v[34:35]
	v_lshl_add_u64 v[34:35], v[140:141], 1, v[34:35]
	s_waitcnt vmcnt(31)
	v_lshlrev_b32_e32 v38, 16, v204
	v_and_b32_e32 v39, 0xffff0000, v204
	v_lshlrev_b32_e32 v36, 16, v205
	v_and_b32_e32 v37, 0xffff0000, v205
	v_pk_add_f32 v[30:31], v[30:31], v[36:37]
	v_pk_add_f32 v[28:29], v[28:29], v[38:39]
	s_nop 0
	v_cvt_pk_bf16_f32 v36, v28, v29
	v_cvt_pk_bf16_f32 v37, v30, v31
	v_mul_f32_e32 v29, v29, v29
	global_store_dwordx2 v[34:35], v[36:37], off
	v_mul_f32_e32 v31, v31, v31
	v_fmac_f32_e32 v29, v28, v28
	v_fmac_f32_e32 v31, v30, v30
	v_add_f32_e32 v28, v29, v31
	s_waitcnt vmcnt(31)
	v_lshlrev_b32_e32 v36, 16, v208
	v_and_b32_e32 v37, 0xffff0000, v208
	v_lshlrev_b32_e32 v38, 16, v209
	v_and_b32_e32 v39, 0xffff0000, v209
	v_pk_add_f32 v[26:27], v[26:27], v[38:39]
	v_pk_add_f32 v[24:25], v[24:25], v[36:37]
	s_nop 0
	v_cvt_pk_bf16_f32 v36, v24, v25
	v_cvt_pk_bf16_f32 v37, v26, v27
	v_mul_f32_e32 v25, v25, v25
	global_store_dwordx2 v[34:35], v[36:37], off offset:32
	v_mul_f32_e32 v27, v27, v27
	v_fmac_f32_e32 v25, v24, v24
	v_fmac_f32_e32 v27, v26, v26
	v_add_f32_e32 v24, v25, v27
	v_add_f32_e32 v24, v28, v24
	s_waitcnt vmcnt(31)
	v_lshlrev_b32_e32 v36, 16, v210
	v_and_b32_e32 v37, 0xffff0000, v210
	v_lshlrev_b32_e32 v38, 16, v211
	v_and_b32_e32 v39, 0xffff0000, v211
	v_pk_add_f32 v[22:23], v[22:23], v[38:39]
	v_pk_add_f32 v[20:21], v[20:21], v[36:37]
	s_nop 0
	v_cvt_pk_bf16_f32 v36, v20, v21
	v_cvt_pk_bf16_f32 v37, v22, v23
	v_mul_f32_e32 v21, v21, v21
	v_mul_f32_e32 v23, v23, v23
	v_fmac_f32_e32 v21, v20, v20
	v_fmac_f32_e32 v23, v22, v22
	v_add_f32_e32 v20, v21, v23
	v_add_f32_e32 v24, v24, v20
	global_store_dwordx2 v[34:35], v[36:37], off offset:256
	s_waitcnt vmcnt(31)
	v_lshlrev_b32_e32 v20, 16, v212
	v_and_b32_e32 v21, 0xffff0000, v212
	v_lshlrev_b32_e32 v22, 16, v213
	v_and_b32_e32 v23, 0xffff0000, v213
	v_pk_add_f32 v[18:19], v[18:19], v[22:23]
	v_pk_add_f32 v[16:17], v[16:17], v[20:21]
	v_mul_f32_e32 v21, v19, v19
	v_mul_f32_e32 v20, v17, v17
	v_fmac_f32_e32 v20, v16, v16
	v_fmac_f32_e32 v21, v18, v18
	v_add_f32_e32 v20, v20, v21
	v_add_f32_e32 v20, v24, v20
	ds_swizzle_b32 v21, v20 offset:swizzle(SWAP,16)
	v_cvt_pk_bf16_f32 v16, v16, v17
	v_cvt_pk_bf16_f32 v17, v18, v19
	global_store_dwordx2 v[34:35], v[16:17], off offset:288
	s_waitcnt lgkmcnt(0)
	v_add_f32_e32 v16, v20, v21
	v_mov_b32_e32 v17, v16
	s_nop 1
	v_permlane32_swap_b32_e32 v16, v17
	s_and_saveexec_b64 s[28:29], s[4:5]
	s_cbranch_execz .LBB0_1289
	v_add_f32_e32 v18, v16, v17
	v_lshlrev_b64 v[16:17], 6, v[32:33]
	v_lshl_add_u64 v[16:17], s[10:11], 0, v[16:17]
	v_lshl_add_u64 v[16:17], s[26:27], 2, v[16:17]
	s_lshl_b32 s2, s48, 2
	v_lshl_add_u64 v[16:17], v[16:17], 0, s[2:3]
	global_store_dword v[16:17], v18, off
.LBB0_1289:
	s_or_b64 exec, exec, s[28:29]
	v_add_u32_e32 v16, 0xb0, v142
	v_ashrrev_i32_e32 v17, 31, v16
	v_lshlrev_b64 v[18:19], 11, v[16:17]
	v_lshl_add_u64 v[18:19], s[8:9], 0, v[18:19]
	v_lshl_add_u64 v[18:19], v[140:141], 1, v[18:19]
	s_waitcnt vmcnt(31)
	v_lshlrev_b32_e32 v22, 16, v214
	v_and_b32_e32 v23, 0xffff0000, v214
	v_lshlrev_b32_e32 v20, 16, v215
	v_and_b32_e32 v21, 0xffff0000, v215
	v_pk_add_f32 v[14:15], v[14:15], v[20:21]
	v_pk_add_f32 v[12:13], v[12:13], v[22:23]
	s_nop 0
	v_cvt_pk_bf16_f32 v20, v12, v13
	v_cvt_pk_bf16_f32 v21, v14, v15
	v_mul_f32_e32 v13, v13, v13
	global_store_dwordx2 v[18:19], v[20:21], off
	v_mul_f32_e32 v15, v15, v15
	v_fmac_f32_e32 v13, v12, v12
	v_fmac_f32_e32 v15, v14, v14
	v_add_f32_e32 v12, v13, v15
	s_waitcnt vmcnt(31)
	v_lshlrev_b32_e32 v20, 16, v216
	v_and_b32_e32 v21, 0xffff0000, v216
	v_lshlrev_b32_e32 v22, 16, v217
	v_and_b32_e32 v23, 0xffff0000, v217
	v_pk_add_f32 v[10:11], v[10:11], v[22:23]
	v_pk_add_f32 v[8:9], v[8:9], v[20:21]
	s_nop 0
	v_cvt_pk_bf16_f32 v20, v8, v9
	v_cvt_pk_bf16_f32 v21, v10, v11
	v_mul_f32_e32 v9, v9, v9
	global_store_dwordx2 v[18:19], v[20:21], off offset:32
	v_mul_f32_e32 v11, v11, v11
	v_fmac_f32_e32 v9, v8, v8
	v_fmac_f32_e32 v11, v10, v10
	v_add_f32_e32 v8, v9, v11
	v_add_f32_e32 v8, v12, v8
	s_waitcnt vmcnt(31)
	v_lshlrev_b32_e32 v20, 16, v218
	v_and_b32_e32 v21, 0xffff0000, v218
	v_lshlrev_b32_e32 v22, 16, v219
	v_and_b32_e32 v23, 0xffff0000, v219
	v_pk_add_f32 v[6:7], v[6:7], v[22:23]
	v_pk_add_f32 v[4:5], v[4:5], v[20:21]
	s_nop 0
	v_cvt_pk_bf16_f32 v20, v4, v5
	v_cvt_pk_bf16_f32 v21, v6, v7
	v_mul_f32_e32 v5, v5, v5
	v_mul_f32_e32 v7, v7, v7
	v_fmac_f32_e32 v5, v4, v4
	v_fmac_f32_e32 v7, v6, v6
	v_add_f32_e32 v4, v5, v7
	v_add_f32_e32 v8, v8, v4
	global_store_dwordx2 v[18:19], v[20:21], off offset:256
	s_waitcnt vmcnt(31)
	v_lshlrev_b32_e32 v4, 16, v220
	v_and_b32_e32 v5, 0xffff0000, v220
	v_lshlrev_b32_e32 v6, 16, v221
	v_and_b32_e32 v7, 0xffff0000, v221
	v_pk_add_f32 v[2:3], v[2:3], v[6:7]
	v_pk_add_f32 v[0:1], v[0:1], v[4:5]
	v_mul_f32_e32 v5, v3, v3
	v_mul_f32_e32 v4, v1, v1
	v_fmac_f32_e32 v4, v0, v0
	v_fmac_f32_e32 v5, v2, v2
	v_add_f32_e32 v4, v4, v5
	v_add_f32_e32 v4, v8, v4
	ds_swizzle_b32 v5, v4 offset:swizzle(SWAP,16)
	v_cvt_pk_bf16_f32 v0, v0, v1
	v_cvt_pk_bf16_f32 v1, v2, v3
	global_store_dwordx2 v[18:19], v[0:1], off offset:288
	s_waitcnt lgkmcnt(0)
	v_add_f32_e32 v0, v4, v5
	v_mov_b32_e32 v1, v0
	s_nop 1
	v_permlane32_swap_b32_e32 v0, v1
	s_and_saveexec_b64 s[28:29], s[4:5]
	s_cbranch_execz .LBB0_1291
	v_add_f32_e32 v2, v0, v1
	v_lshlrev_b64 v[0:1], 6, v[16:17]
	v_lshl_add_u64 v[0:1], s[10:11], 0, v[0:1]
	v_lshl_add_u64 v[0:1], s[26:27], 2, v[0:1]
	s_lshl_b32 s2, s48, 2
	v_lshl_add_u64 v[0:1], v[0:1], 0, s[2:3]
	global_store_dword v[0:1], v2, off

.LBB0_1447:
	v_lshl_add_u32 v142, s26, 8, v144
	v_ashrrev_i32_e32 v143, 31, v142
	v_lshl_or_b32 v140, s2, 8, v146
	v_lshlrev_b64 v[150:151], 11, v[142:143]
	v_ashrrev_i32_e32 v141, 31, v140
	v_lshl_add_u64 v[150:151], s[10:11], 0, v[150:151]
	v_lshl_add_u64 v[150:151], v[140:141], 1, v[150:151]
	s_mov_b64 s[98:99], 0x8000
	s_mov_b64 s[100:101], 0x28000
	global_load_dwordx2 v[156:157], v[150:151], off
	global_load_dwordx2 v[158:159], v[150:151], off offset:32
	global_load_dwordx2 v[160:161], v[150:151], off offset:256
	global_load_dwordx2 v[162:163], v[150:151], off offset:288
	v_lshl_add_u64 v[222:223], v[150:151], 0, s[98:99]
	global_load_dwordx2 v[164:165], v[222:223], off
	global_load_dwordx2 v[166:167], v[222:223], off offset:32
	global_load_dwordx2 v[168:169], v[222:223], off offset:256
	global_load_dwordx2 v[170:171], v[222:223], off offset:288
	v_lshl_add_u64 v[222:223], v[222:223], 0, s[98:99]
	global_load_dwordx2 v[172:173], v[222:223], off
	global_load_dwordx2 v[174:175], v[222:223], off offset:32
	global_load_dwordx2 v[176:177], v[222:223], off offset:256
	global_load_dwordx2 v[178:179], v[222:223], off offset:288
	v_lshl_add_u64 v[222:223], v[222:223], 0, s[98:99]
	global_load_dwordx2 v[180:181], v[222:223], off
	global_load_dwordx2 v[182:183], v[222:223], off offset:32
	global_load_dwordx2 v[184:185], v[222:223], off offset:256
	global_load_dwordx2 v[186:187], v[222:223], off offset:288
	v_lshl_add_u64 v[222:223], v[222:223], 0, s[100:101]
	global_load_dwordx2 v[188:189], v[222:223], off
	global_load_dwordx2 v[190:191], v[222:223], off offset:32
	global_load_dwordx2 v[192:193], v[222:223], off offset:256
	global_load_dwordx2 v[194:195], v[222:223], off offset:288
	v_lshl_add_u64 v[222:223], v[222:223], 0, s[98:99]
	global_load_dwordx2 v[196:197], v[222:223], off
	global_load_dwordx2 v[198:199], v[222:223], off offset:32
	global_load_dwordx2 v[200:201], v[222:223], off offset:256
	global_load_dwordx2 v[202:203], v[222:223], off offset:288
	v_lshl_add_u64 v[222:223], v[222:223], 0, s[98:99]
	global_load_dwordx2 v[204:205], v[222:223], off
	global_load_dwordx2 v[208:209], v[222:223], off offset:32
	global_load_dwordx2 v[210:211], v[222:223], off offset:256
	global_load_dwordx2 v[212:213], v[222:223], off offset:288
	v_lshl_add_u64 v[222:223], v[222:223], 0, s[98:99]
	global_load_dwordx2 v[214:215], v[222:223], off
	global_load_dwordx2 v[216:217], v[222:223], off offset:32
	global_load_dwordx2 v[218:219], v[222:223], off offset:256
	global_load_dwordx2 v[220:221], v[222:223], off offset:288
	s_lshl_b32 s26, s2, 2
	s_ashr_i32 s27, s26, 31
	s_waitcnt vmcnt(31)
	v_lshlrev_b32_e32 v154, 16, v156
	v_and_b32_e32 v155, 0xffff0000, v156
	v_lshlrev_b32_e32 v152, 16, v157
	v_and_b32_e32 v153, 0xffff0000, v157
	v_pk_add_f32 v[126:127], v[126:127], v[152:153]
	v_pk_add_f32 v[124:125], v[124:125], v[154:155]
	s_nop 0
	v_cvt_pk_bf16_f32 v152, v124, v125
	v_cvt_pk_bf16_f32 v153, v126, v127
	v_mul_f32_e32 v125, v125, v125
	global_store_dwordx2 v[150:151], v[152:153], off
	v_mul_f32_e32 v127, v127, v127
	v_fmac_f32_e32 v125, v124, v124
	v_fmac_f32_e32 v127, v126, v126
	v_add_f32_e32 v124, v125, v127
	s_waitcnt vmcnt(31)
	v_lshlrev_b32_e32 v152, 16, v158
	v_and_b32_e32 v153, 0xffff0000, v158
	v_lshlrev_b32_e32 v154, 16, v159
	v_and_b32_e32 v155, 0xffff0000, v159
	v_pk_add_f32 v[122:123], v[122:123], v[154:155]
	v_pk_add_f32 v[120:121], v[120:121], v[152:153]
	s_nop 0
	v_cvt_pk_bf16_f32 v152, v120, v121
	v_cvt_pk_bf16_f32 v153, v122, v123
	v_mul_f32_e32 v121, v121, v121
	global_store_dwordx2 v[150:151], v[152:153], off offset:32
	v_mul_f32_e32 v123, v123, v123
	v_fmac_f32_e32 v121, v120, v120
	v_fmac_f32_e32 v123, v122, v122
	v_add_f32_e32 v120, v121, v123
	v_add_f32_e32 v120, v124, v120
	s_waitcnt vmcnt(31)
	v_lshlrev_b32_e32 v152, 16, v160
	v_and_b32_e32 v153, 0xffff0000, v160
	v_lshlrev_b32_e32 v154, 16, v161
	v_and_b32_e32 v155, 0xffff0000, v161
	v_pk_add_f32 v[118:119], v[118:119], v[154:155]
	v_pk_add_f32 v[116:117], v[116:117], v[152:153]
	s_nop 0
	v_cvt_pk_bf16_f32 v152, v116, v117
	v_cvt_pk_bf16_f32 v153, v118, v119
	v_mul_f32_e32 v117, v117, v117
	v_mul_f32_e32 v119, v119, v119
	v_fmac_f32_e32 v117, v116, v116
	v_fmac_f32_e32 v119, v118, v118
	v_add_f32_e32 v116, v117, v119
	v_add_f32_e32 v120, v120, v116
	global_store_dwordx2 v[150:151], v[152:153], off offset:256
	s_waitcnt vmcnt(31)
	v_lshlrev_b32_e32 v116, 16, v162
	v_and_b32_e32 v117, 0xffff0000, v162
	v_lshlrev_b32_e32 v118, 16, v163
	v_and_b32_e32 v119, 0xffff0000, v163
	v_pk_add_f32 v[114:115], v[114:115], v[118:119]
	v_pk_add_f32 v[112:113], v[112:113], v[116:117]
	v_mul_f32_e32 v117, v115, v115
	v_mul_f32_e32 v116, v113, v113
	v_fmac_f32_e32 v116, v112, v112
	v_fmac_f32_e32 v117, v114, v114
	v_add_f32_e32 v116, v116, v117
	v_add_f32_e32 v116, v120, v116
	ds_swizzle_b32 v117, v116 offset:swizzle(SWAP,16)
	v_cvt_pk_bf16_f32 v112, v112, v113
	v_cvt_pk_bf16_f32 v113, v114, v115
	global_store_dwordx2 v[150:151], v[112:113], off offset:288
	s_waitcnt lgkmcnt(0)
	v_add_f32_e32 v112, v116, v117
	v_mov_b32_e32 v113, v112
	s_nop 1
	v_permlane32_swap_b32_e32 v112, v113
	s_and_saveexec_b64 s[28:29], s[4:5]
	s_cbranch_execz .LBB0_1449
	v_add_f32_e32 v114, v112, v113
	v_lshlrev_b64 v[112:113], 6, v[142:143]
	v_lshl_add_u64 v[112:113], s[12:13], 0, v[112:113]
	v_lshl_add_u64 v[112:113], s[26:27], 2, v[112:113]
	s_lshl_b32 s2, s48, 2
	v_lshl_add_u64 v[112:113], v[112:113], 0, s[2:3]
	global_store_dword v[112:113], v114, off
.LBB0_1449:
	s_or_b64 exec, exec, s[28:29]
	v_or_b32_e32 v112, 16, v142
	v_ashrrev_i32_e32 v113, 31, v112
	v_lshlrev_b64 v[114:115], 11, v[112:113]
	v_lshl_add_u64 v[114:115], s[10:11], 0, v[114:115]
	v_lshl_add_u64 v[114:115], v[140:141], 1, v[114:115]
	s_waitcnt vmcnt(31)
	v_lshlrev_b32_e32 v118, 16, v164
	v_and_b32_e32 v119, 0xffff0000, v164
	v_lshlrev_b32_e32 v116, 16, v165
	v_and_b32_e32 v117, 0xffff0000, v165
	v_pk_add_f32 v[110:111], v[110:111], v[116:117]
	v_pk_add_f32 v[108:109], v[108:109], v[118:119]
	s_nop 0
	v_cvt_pk_bf16_f32 v116, v108, v109
	v_cvt_pk_bf16_f32 v117, v110, v111
	v_mul_f32_e32 v109, v109, v109
	global_store_dwordx2 v[114:115], v[116:117], off
	v_mul_f32_e32 v111, v111, v111
	v_fmac_f32_e32 v109, v108, v108
	v_fmac_f32_e32 v111, v110, v110
	v_add_f32_e32 v108, v109, v111
	s_waitcnt vmcnt(31)
	v_lshlrev_b32_e32 v116, 16, v166
	v_and_b32_e32 v117, 0xffff0000, v166
	v_lshlrev_b32_e32 v118, 16, v167
	v_and_b32_e32 v119, 0xffff0000, v167
	v_pk_add_f32 v[106:107], v[106:107], v[118:119]
	v_pk_add_f32 v[104:105], v[104:105], v[116:117]
	s_nop 0
	v_cvt_pk_bf16_f32 v116, v104, v105
	v_cvt_pk_bf16_f32 v117, v106, v107
	v_mul_f32_e32 v105, v105, v105
	global_store_dwordx2 v[114:115], v[116:117], off offset:32
	v_mul_f32_e32 v107, v107, v107
	v_fmac_f32_e32 v105, v104, v104
	v_fmac_f32_e32 v107, v106, v106
	v_add_f32_e32 v104, v105, v107
	v_add_f32_e32 v104, v108, v104
	s_waitcnt vmcnt(31)
	v_lshlrev_b32_e32 v116, 16, v168
	v_and_b32_e32 v117, 0xffff0000, v168
	v_lshlrev_b32_e32 v118, 16, v169
	v_and_b32_e32 v119, 0xffff0000, v169
	v_pk_add_f32 v[102:103], v[102:103], v[118:119]
	v_pk_add_f32 v[100:101], v[100:101], v[116:117]
	s_nop 0
	v_cvt_pk_bf16_f32 v116, v100, v101
	v_cvt_pk_bf16_f32 v117, v102, v103
	v_mul_f32_e32 v101, v101, v101
	v_mul_f32_e32 v103, v103, v103
	v_fmac_f32_e32 v101, v100, v100
	v_fmac_f32_e32 v103, v102, v102
	v_add_f32_e32 v100, v101, v103
	v_add_f32_e32 v104, v104, v100
	global_store_dwordx2 v[114:115], v[116:117], off offset:256
	s_waitcnt vmcnt(31)
	v_lshlrev_b32_e32 v100, 16, v170
	v_and_b32_e32 v101, 0xffff0000, v170
	v_lshlrev_b32_e32 v102, 16, v171
	v_and_b32_e32 v103, 0xffff0000, v171
	v_pk_add_f32 v[98:99], v[98:99], v[102:103]
	v_pk_add_f32 v[96:97], v[96:97], v[100:101]
	v_mul_f32_e32 v101, v99, v99
	v_mul_f32_e32 v100, v97, v97
	v_fmac_f32_e32 v100, v96, v96
	v_fmac_f32_e32 v101, v98, v98
	v_add_f32_e32 v100, v100, v101
	v_add_f32_e32 v100, v104, v100
	ds_swizzle_b32 v101, v100 offset:swizzle(SWAP,16)
	v_cvt_pk_bf16_f32 v96, v96, v97
	v_cvt_pk_bf16_f32 v97, v98, v99
	global_store_dwordx2 v[114:115], v[96:97], off offset:288
	s_waitcnt lgkmcnt(0)
	v_add_f32_e32 v96, v100, v101
	v_mov_b32_e32 v97, v96
	s_nop 1
	v_permlane32_swap_b32_e32 v96, v97
	s_and_saveexec_b64 s[28:29], s[4:5]
	s_cbranch_execz .LBB0_1451
	v_add_f32_e32 v98, v96, v97
	v_lshlrev_b64 v[96:97], 6, v[112:113]
	v_lshl_add_u64 v[96:97], s[12:13], 0, v[96:97]
	v_lshl_add_u64 v[96:97], s[26:27], 2, v[96:97]
	s_lshl_b32 s2, s48, 2
	v_lshl_add_u64 v[96:97], v[96:97], 0, s[2:3]
	global_store_dword v[96:97], v98, off
.LBB0_1451:
	s_or_b64 exec, exec, s[28:29]
	v_or_b32_e32 v96, 32, v142
	v_ashrrev_i32_e32 v97, 31, v96
	v_lshlrev_b64 v[98:99], 11, v[96:97]
	v_lshl_add_u64 v[98:99], s[10:11], 0, v[98:99]
	v_lshl_add_u64 v[98:99], v[140:141], 1, v[98:99]
	s_waitcnt vmcnt(31)
	v_lshlrev_b32_e32 v102, 16, v172
	v_and_b32_e32 v103, 0xffff0000, v172
	v_lshlrev_b32_e32 v100, 16, v173
	v_and_b32_e32 v101, 0xffff0000, v173
	v_pk_add_f32 v[94:95], v[94:95], v[100:101]
	v_pk_add_f32 v[92:93], v[92:93], v[102:103]
	s_nop 0
	v_cvt_pk_bf16_f32 v100, v92, v93
	v_cvt_pk_bf16_f32 v101, v94, v95
	v_mul_f32_e32 v93, v93, v93
	global_store_dwordx2 v[98:99], v[100:101], off
	v_mul_f32_e32 v95, v95, v95
	v_fmac_f32_e32 v93, v92, v92
	v_fmac_f32_e32 v95, v94, v94
	v_add_f32_e32 v92, v93, v95
	s_waitcnt vmcnt(31)
	v_lshlrev_b32_e32 v100, 16, v174
	v_and_b32_e32 v101, 0xffff0000, v174
	v_lshlrev_b32_e32 v102, 16, v175
	v_and_b32_e32 v103, 0xffff0000, v175
	v_pk_add_f32 v[90:91], v[90:91], v[102:103]
	v_pk_add_f32 v[88:89], v[88:89], v[100:101]
	s_nop 0
	v_cvt_pk_bf16_f32 v100, v88, v89
	v_cvt_pk_bf16_f32 v101, v90, v91
	v_mul_f32_e32 v89, v89, v89
	global_store_dwordx2 v[98:99], v[100:101], off offset:32
	v_mul_f32_e32 v91, v91, v91
	v_fmac_f32_e32 v89, v88, v88
	v_fmac_f32_e32 v91, v90, v90
	v_add_f32_e32 v88, v89, v91
	v_add_f32_e32 v88, v92, v88
	s_waitcnt vmcnt(31)
	v_lshlrev_b32_e32 v100, 16, v176
	v_and_b32_e32 v101, 0xffff0000, v176
	v_lshlrev_b32_e32 v102, 16, v177
	v_and_b32_e32 v103, 0xffff0000, v177
	v_pk_add_f32 v[86:87], v[86:87], v[102:103]
	v_pk_add_f32 v[84:85], v[84:85], v[100:101]
	s_nop 0
	v_cvt_pk_bf16_f32 v100, v84, v85
	v_cvt_pk_bf16_f32 v101, v86, v87
	v_mul_f32_e32 v85, v85, v85
	v_mul_f32_e32 v87, v87, v87
	v_fmac_f32_e32 v85, v84, v84
	v_fmac_f32_e32 v87, v86, v86
	v_add_f32_e32 v84, v85, v87
	v_add_f32_e32 v88, v88, v84
	global_store_dwordx2 v[98:99], v[100:101], off offset:256
	s_waitcnt vmcnt(31)
	v_lshlrev_b32_e32 v84, 16, v178
	v_and_b32_e32 v85, 0xffff0000, v178
	v_lshlrev_b32_e32 v86, 16, v179
	v_and_b32_e32 v87, 0xffff0000, v179
	v_pk_add_f32 v[82:83], v[82:83], v[86:87]
	v_pk_add_f32 v[80:81], v[80:81], v[84:85]
	v_mul_f32_e32 v85, v83, v83
	v_mul_f32_e32 v84, v81, v81
	v_fmac_f32_e32 v84, v80, v80
	v_fmac_f32_e32 v85, v82, v82
	v_add_f32_e32 v84, v84, v85
	v_add_f32_e32 v84, v88, v84
	ds_swizzle_b32 v85, v84 offset:swizzle(SWAP,16)
	v_cvt_pk_bf16_f32 v80, v80, v81
	v_cvt_pk_bf16_f32 v81, v82, v83
	global_store_dwordx2 v[98:99], v[80:81], off offset:288
	s_waitcnt lgkmcnt(0)
	v_add_f32_e32 v80, v84, v85
	v_mov_b32_e32 v81, v80
	s_nop 1
	v_permlane32_swap_b32_e32 v80, v81
	s_and_saveexec_b64 s[28:29], s[4:5]
	s_cbranch_execz .LBB0_1453
	v_add_f32_e32 v82, v80, v81
	v_lshlrev_b64 v[80:81], 6, v[96:97]
	v_lshl_add_u64 v[80:81], s[12:13], 0, v[80:81]
	v_lshl_add_u64 v[80:81], s[26:27], 2, v[80:81]
	s_lshl_b32 s2, s48, 2
	v_lshl_add_u64 v[80:81], v[80:81], 0, s[2:3]
	global_store_dword v[80:81], v82, off
.LBB0_1453:
	s_or_b64 exec, exec, s[28:29]
	v_or_b32_e32 v80, 48, v142
	v_ashrrev_i32_e32 v81, 31, v80
	v_lshlrev_b64 v[82:83], 11, v[80:81]
	v_lshl_add_u64 v[82:83], s[10:11], 0, v[82:83]
	v_lshl_add_u64 v[82:83], v[140:141], 1, v[82:83]
	s_waitcnt vmcnt(31)
	v_lshlrev_b32_e32 v86, 16, v180
	v_and_b32_e32 v87, 0xffff0000, v180
	v_lshlrev_b32_e32 v84, 16, v181
	v_and_b32_e32 v85, 0xffff0000, v181
	v_pk_add_f32 v[78:79], v[78:79], v[84:85]
	v_pk_add_f32 v[76:77], v[76:77], v[86:87]
	s_nop 0
	v_cvt_pk_bf16_f32 v84, v76, v77
	v_cvt_pk_bf16_f32 v85, v78, v79
	v_mul_f32_e32 v77, v77, v77
	global_store_dwordx2 v[82:83], v[84:85], off
	v_mul_f32_e32 v79, v79, v79
	v_fmac_f32_e32 v77, v76, v76
	v_fmac_f32_e32 v79, v78, v78
	v_add_f32_e32 v76, v77, v79
	s_waitcnt vmcnt(31)
	v_lshlrev_b32_e32 v84, 16, v182
	v_and_b32_e32 v85, 0xffff0000, v182
	v_lshlrev_b32_e32 v86, 16, v183
	v_and_b32_e32 v87, 0xffff0000, v183
	v_pk_add_f32 v[74:75], v[74:75], v[86:87]
	v_pk_add_f32 v[72:73], v[72:73], v[84:85]
	s_nop 0
	v_cvt_pk_bf16_f32 v84, v72, v73
	v_cvt_pk_bf16_f32 v85, v74, v75
	v_mul_f32_e32 v73, v73, v73
	global_store_dwordx2 v[82:83], v[84:85], off offset:32
	v_mul_f32_e32 v75, v75, v75
	v_fmac_f32_e32 v73, v72, v72
	v_fmac_f32_e32 v75, v74, v74
	v_add_f32_e32 v72, v73, v75
	v_add_f32_e32 v72, v76, v72
	s_waitcnt vmcnt(31)
	v_lshlrev_b32_e32 v84, 16, v184
	v_and_b32_e32 v85, 0xffff0000, v184
	v_lshlrev_b32_e32 v86, 16, v185
	v_and_b32_e32 v87, 0xffff0000, v185
	v_pk_add_f32 v[70:71], v[70:71], v[86:87]
	v_pk_add_f32 v[68:69], v[68:69], v[84:85]
	s_nop 0
	v_cvt_pk_bf16_f32 v84, v68, v69
	v_cvt_pk_bf16_f32 v85, v70, v71
	v_mul_f32_e32 v69, v69, v69
	v_mul_f32_e32 v71, v71, v71
	v_fmac_f32_e32 v69, v68, v68
	v_fmac_f32_e32 v71, v70, v70
	v_add_f32_e32 v68, v69, v71
	v_add_f32_e32 v72, v72, v68
	global_store_dwordx2 v[82:83], v[84:85], off offset:256
	s_waitcnt vmcnt(31)
	v_lshlrev_b32_e32 v68, 16, v186
	v_and_b32_e32 v69, 0xffff0000, v186
	v_lshlrev_b32_e32 v70, 16, v187
	v_and_b32_e32 v71, 0xffff0000, v187
	v_pk_add_f32 v[66:67], v[66:67], v[70:71]
	v_pk_add_f32 v[64:65], v[64:65], v[68:69]
	v_mul_f32_e32 v69, v67, v67
	v_mul_f32_e32 v68, v65, v65
	v_fmac_f32_e32 v68, v64, v64
	v_fmac_f32_e32 v69, v66, v66
	v_add_f32_e32 v68, v68, v69
	v_add_f32_e32 v68, v72, v68
	ds_swizzle_b32 v69, v68 offset:swizzle(SWAP,16)
	v_cvt_pk_bf16_f32 v64, v64, v65
	v_cvt_pk_bf16_f32 v65, v66, v67
	global_store_dwordx2 v[82:83], v[64:65], off offset:288
	s_waitcnt lgkmcnt(0)
	v_add_f32_e32 v64, v68, v69
	v_mov_b32_e32 v65, v64
	s_nop 1
	v_permlane32_swap_b32_e32 v64, v65
	s_and_saveexec_b64 s[28:29], s[4:5]
	s_cbranch_execz .LBB0_1455
	v_add_f32_e32 v66, v64, v65
	v_lshlrev_b64 v[64:65], 6, v[80:81]
	v_lshl_add_u64 v[64:65], s[12:13], 0, v[64:65]
	v_lshl_add_u64 v[64:65], s[26:27], 2, v[64:65]
	s_lshl_b32 s2, s48, 2
	v_lshl_add_u64 v[64:65], v[64:65], 0, s[2:3]
	global_store_dword v[64:65], v66, off
.LBB0_1455:
	s_or_b64 exec, exec, s[28:29]
	v_add_u32_e32 v64, 0x80, v142
	v_ashrrev_i32_e32 v65, 31, v64
	v_lshlrev_b64 v[66:67], 11, v[64:65]
	v_lshl_add_u64 v[66:67], s[10:11], 0, v[66:67]
	v_lshl_add_u64 v[66:67], v[140:141], 1, v[66:67]
	s_waitcnt vmcnt(31)
	v_lshlrev_b32_e32 v70, 16, v188
	v_and_b32_e32 v71, 0xffff0000, v188
	v_lshlrev_b32_e32 v68, 16, v189
	v_and_b32_e32 v69, 0xffff0000, v189
	v_pk_add_f32 v[62:63], v[62:63], v[68:69]
	v_pk_add_f32 v[60:61], v[60:61], v[70:71]
	s_nop 0
	v_cvt_pk_bf16_f32 v68, v60, v61
	v_cvt_pk_bf16_f32 v69, v62, v63
	v_mul_f32_e32 v61, v61, v61
	global_store_dwordx2 v[66:67], v[68:69], off
	v_mul_f32_e32 v63, v63, v63
	v_fmac_f32_e32 v61, v60, v60
	v_fmac_f32_e32 v63, v62, v62
	v_add_f32_e32 v60, v61, v63
	s_waitcnt vmcnt(31)
	v_lshlrev_b32_e32 v68, 16, v190
	v_and_b32_e32 v69, 0xffff0000, v190
	v_lshlrev_b32_e32 v70, 16, v191
	v_and_b32_e32 v71, 0xffff0000, v191
	v_pk_add_f32 v[58:59], v[58:59], v[70:71]
	v_pk_add_f32 v[56:57], v[56:57], v[68:69]
	s_nop 0
	v_cvt_pk_bf16_f32 v68, v56, v57
	v_cvt_pk_bf16_f32 v69, v58, v59
	v_mul_f32_e32 v57, v57, v57
	global_store_dwordx2 v[66:67], v[68:69], off offset:32
	v_mul_f32_e32 v59, v59, v59
	v_fmac_f32_e32 v57, v56, v56
	v_fmac_f32_e32 v59, v58, v58
	v_add_f32_e32 v56, v57, v59
	v_add_f32_e32 v56, v60, v56
	s_waitcnt vmcnt(31)
	v_lshlrev_b32_e32 v68, 16, v192
	v_and_b32_e32 v69, 0xffff0000, v192
	v_lshlrev_b32_e32 v70, 16, v193
	v_and_b32_e32 v71, 0xffff0000, v193
	v_pk_add_f32 v[54:55], v[54:55], v[70:71]
	v_pk_add_f32 v[52:53], v[52:53], v[68:69]
	s_nop 0
	v_cvt_pk_bf16_f32 v68, v52, v53
	v_cvt_pk_bf16_f32 v69, v54, v55
	v_mul_f32_e32 v53, v53, v53
	v_mul_f32_e32 v55, v55, v55
	v_fmac_f32_e32 v53, v52, v52
	v_fmac_f32_e32 v55, v54, v54
	v_add_f32_e32 v52, v53, v55
	v_add_f32_e32 v56, v56, v52
	global_store_dwordx2 v[66:67], v[68:69], off offset:256
	s_waitcnt vmcnt(31)
	v_lshlrev_b32_e32 v52, 16, v194
	v_and_b32_e32 v53, 0xffff0000, v194
	v_lshlrev_b32_e32 v54, 16, v195
	v_and_b32_e32 v55, 0xffff0000, v195
	v_pk_add_f32 v[50:51], v[50:51], v[54:55]
	v_pk_add_f32 v[48:49], v[48:49], v[52:53]
	v_mul_f32_e32 v53, v51, v51
	v_mul_f32_e32 v52, v49, v49
	v_fmac_f32_e32 v52, v48, v48
	v_fmac_f32_e32 v53, v50, v50
	v_add_f32_e32 v52, v52, v53
	v_add_f32_e32 v52, v56, v52
	ds_swizzle_b32 v53, v52 offset:swizzle(SWAP,16)
	v_cvt_pk_bf16_f32 v48, v48, v49
	v_cvt_pk_bf16_f32 v49, v50, v51
	global_store_dwordx2 v[66:67], v[48:49], off offset:288
	s_waitcnt lgkmcnt(0)
	v_add_f32_e32 v48, v52, v53
	v_mov_b32_e32 v49, v48
	s_nop 1
	v_permlane32_swap_b32_e32 v48, v49
	s_and_saveexec_b64 s[28:29], s[4:5]
	s_cbranch_execz .LBB0_1457
	v_add_f32_e32 v50, v48, v49
	v_lshlrev_b64 v[48:49], 6, v[64:65]
	v_lshl_add_u64 v[48:49], s[12:13], 0, v[48:49]
	v_lshl_add_u64 v[48:49], s[26:27], 2, v[48:49]
	s_lshl_b32 s2, s48, 2
	v_lshl_add_u64 v[48:49], v[48:49], 0, s[2:3]
	global_store_dword v[48:49], v50, off
.LBB0_1457:
	s_or_b64 exec, exec, s[28:29]
	v_add_u32_e32 v48, 0x90, v142
	v_ashrrev_i32_e32 v49, 31, v48
	v_lshlrev_b64 v[50:51], 11, v[48:49]
	v_lshl_add_u64 v[50:51], s[10:11], 0, v[50:51]
	v_lshl_add_u64 v[50:51], v[140:141], 1, v[50:51]
	s_waitcnt vmcnt(31)
	v_lshlrev_b32_e32 v54, 16, v196
	v_and_b32_e32 v55, 0xffff0000, v196
	v_lshlrev_b32_e32 v52, 16, v197
	v_and_b32_e32 v53, 0xffff0000, v197
	v_pk_add_f32 v[46:47], v[46:47], v[52:53]
	v_pk_add_f32 v[44:45], v[44:45], v[54:55]
	s_nop 0
	v_cvt_pk_bf16_f32 v52, v44, v45
	v_cvt_pk_bf16_f32 v53, v46, v47
	v_mul_f32_e32 v45, v45, v45
	global_store_dwordx2 v[50:51], v[52:53], off
	v_mul_f32_e32 v47, v47, v47
	v_fmac_f32_e32 v45, v44, v44
	v_fmac_f32_e32 v47, v46, v46
	v_add_f32_e32 v44, v45, v47
	s_waitcnt vmcnt(31)
	v_lshlrev_b32_e32 v52, 16, v198
	v_and_b32_e32 v53, 0xffff0000, v198
	v_lshlrev_b32_e32 v54, 16, v199
	v_and_b32_e32 v55, 0xffff0000, v199
	v_pk_add_f32 v[42:43], v[42:43], v[54:55]
	v_pk_add_f32 v[40:41], v[40:41], v[52:53]
	s_nop 0
	v_cvt_pk_bf16_f32 v52, v40, v41
	v_cvt_pk_bf16_f32 v53, v42, v43
	v_mul_f32_e32 v41, v41, v41
	global_store_dwordx2 v[50:51], v[52:53], off offset:32
	v_mul_f32_e32 v43, v43, v43
	v_fmac_f32_e32 v41, v40, v40
	v_fmac_f32_e32 v43, v42, v42
	v_add_f32_e32 v40, v41, v43
	v_add_f32_e32 v40, v44, v40
	s_waitcnt vmcnt(31)
	v_lshlrev_b32_e32 v52, 16, v200
	v_and_b32_e32 v53, 0xffff0000, v200
	v_lshlrev_b32_e32 v54, 16, v201
	v_and_b32_e32 v55, 0xffff0000, v201
	v_pk_add_f32 v[38:39], v[38:39], v[54:55]
	v_pk_add_f32 v[36:37], v[36:37], v[52:53]
	s_nop 0
	v_cvt_pk_bf16_f32 v52, v36, v37
	v_cvt_pk_bf16_f32 v53, v38, v39
	v_mul_f32_e32 v37, v37, v37
	v_mul_f32_e32 v39, v39, v39
	v_fmac_f32_e32 v37, v36, v36
	v_fmac_f32_e32 v39, v38, v38
	v_add_f32_e32 v36, v37, v39
	v_add_f32_e32 v40, v40, v36
	global_store_dwordx2 v[50:51], v[52:53], off offset:256
	s_waitcnt vmcnt(31)
	v_lshlrev_b32_e32 v36, 16, v202
	v_and_b32_e32 v37, 0xffff0000, v202
	v_lshlrev_b32_e32 v38, 16, v203
	v_and_b32_e32 v39, 0xffff0000, v203
	v_pk_add_f32 v[34:35], v[34:35], v[38:39]
	v_pk_add_f32 v[32:33], v[32:33], v[36:37]
	v_mul_f32_e32 v37, v35, v35
	v_mul_f32_e32 v36, v33, v33
	v_fmac_f32_e32 v36, v32, v32
	v_fmac_f32_e32 v37, v34, v34
	v_add_f32_e32 v36, v36, v37
	v_add_f32_e32 v36, v40, v36
	ds_swizzle_b32 v37, v36 offset:swizzle(SWAP,16)
	v_cvt_pk_bf16_f32 v32, v32, v33
	v_cvt_pk_bf16_f32 v33, v34, v35
	global_store_dwordx2 v[50:51], v[32:33], off offset:288
	s_waitcnt lgkmcnt(0)
	v_add_f32_e32 v32, v36, v37
	v_mov_b32_e32 v33, v32
	s_nop 1
	v_permlane32_swap_b32_e32 v32, v33
	s_and_saveexec_b64 s[28:29], s[4:5]
	s_cbranch_execz .LBB0_1459
	v_add_f32_e32 v34, v32, v33
	v_lshlrev_b64 v[32:33], 6, v[48:49]
	v_lshl_add_u64 v[32:33], s[12:13], 0, v[32:33]
	v_lshl_add_u64 v[32:33], s[26:27], 2, v[32:33]
	s_lshl_b32 s2, s48, 2
	v_lshl_add_u64 v[32:33], v[32:33], 0, s[2:3]
	global_store_dword v[32:33], v34, off
.LBB0_1459:
	s_or_b64 exec, exec, s[28:29]
	v_add_u32_e32 v32, 0xa0, v142
	v_ashrrev_i32_e32 v33, 31, v32
	v_lshlrev_b64 v[34:35], 11, v[32:33]
	v_lshl_add_u64 v[34:35], s[10:11], 0, v[34:35]
	v_lshl_add_u64 v[34:35], v[140:141], 1, v[34:35]
	s_waitcnt vmcnt(31)
	v_lshlrev_b32_e32 v38, 16, v204
	v_and_b32_e32 v39, 0xffff0000, v204
	v_lshlrev_b32_e32 v36, 16, v205
	v_and_b32_e32 v37, 0xffff0000, v205
	v_pk_add_f32 v[30:31], v[30:31], v[36:37]
	v_pk_add_f32 v[28:29], v[28:29], v[38:39]
	s_nop 0
	v_cvt_pk_bf16_f32 v36, v28, v29
	v_cvt_pk_bf16_f32 v37, v30, v31
	v_mul_f32_e32 v29, v29, v29
	global_store_dwordx2 v[34:35], v[36:37], off
	v_mul_f32_e32 v31, v31, v31
	v_fmac_f32_e32 v29, v28, v28
	v_fmac_f32_e32 v31, v30, v30
	v_add_f32_e32 v28, v29, v31
	s_waitcnt vmcnt(31)
	v_lshlrev_b32_e32 v36, 16, v208
	v_and_b32_e32 v37, 0xffff0000, v208
	v_lshlrev_b32_e32 v38, 16, v209
	v_and_b32_e32 v39, 0xffff0000, v209
	v_pk_add_f32 v[26:27], v[26:27], v[38:39]
	v_pk_add_f32 v[24:25], v[24:25], v[36:37]
	s_nop 0
	v_cvt_pk_bf16_f32 v36, v24, v25
	v_cvt_pk_bf16_f32 v37, v26, v27
	v_mul_f32_e32 v25, v25, v25
	global_store_dwordx2 v[34:35], v[36:37], off offset:32
	v_mul_f32_e32 v27, v27, v27
	v_fmac_f32_e32 v25, v24, v24
	v_fmac_f32_e32 v27, v26, v26
	v_add_f32_e32 v24, v25, v27
	v_add_f32_e32 v24, v28, v24
	s_waitcnt vmcnt(31)
	v_lshlrev_b32_e32 v36, 16, v210
	v_and_b32_e32 v37, 0xffff0000, v210
	v_lshlrev_b32_e32 v38, 16, v211
	v_and_b32_e32 v39, 0xffff0000, v211
	v_pk_add_f32 v[22:23], v[22:23], v[38:39]
	v_pk_add_f32 v[20:21], v[20:21], v[36:37]
	s_nop 0
	v_cvt_pk_bf16_f32 v36, v20, v21
	v_cvt_pk_bf16_f32 v37, v22, v23
	v_mul_f32_e32 v21, v21, v21
	v_mul_f32_e32 v23, v23, v23
	v_fmac_f32_e32 v21, v20, v20
	v_fmac_f32_e32 v23, v22, v22
	v_add_f32_e32 v20, v21, v23
	v_add_f32_e32 v24, v24, v20
	global_store_dwordx2 v[34:35], v[36:37], off offset:256
	s_waitcnt vmcnt(31)
	v_lshlrev_b32_e32 v20, 16, v212
	v_and_b32_e32 v21, 0xffff0000, v212
	v_lshlrev_b32_e32 v22, 16, v213
	v_and_b32_e32 v23, 0xffff0000, v213
	v_pk_add_f32 v[18:19], v[18:19], v[22:23]
	v_pk_add_f32 v[16:17], v[16:17], v[20:21]
	v_mul_f32_e32 v21, v19, v19
	v_mul_f32_e32 v20, v17, v17
	v_fmac_f32_e32 v20, v16, v16
	v_fmac_f32_e32 v21, v18, v18
	v_add_f32_e32 v20, v20, v21
	v_add_f32_e32 v20, v24, v20
	ds_swizzle_b32 v21, v20 offset:swizzle(SWAP,16)
	v_cvt_pk_bf16_f32 v16, v16, v17
	v_cvt_pk_bf16_f32 v17, v18, v19
	global_store_dwordx2 v[34:35], v[16:17], off offset:288
	s_waitcnt lgkmcnt(0)
	v_add_f32_e32 v16, v20, v21
	v_mov_b32_e32 v17, v16
	s_nop 1
	v_permlane32_swap_b32_e32 v16, v17
	s_and_saveexec_b64 s[28:29], s[4:5]
	s_cbranch_execz .LBB0_1461
	v_add_f32_e32 v18, v16, v17
	v_lshlrev_b64 v[16:17], 6, v[32:33]
	v_lshl_add_u64 v[16:17], s[12:13], 0, v[16:17]
	v_lshl_add_u64 v[16:17], s[26:27], 2, v[16:17]
	s_lshl_b32 s2, s48, 2
	v_lshl_add_u64 v[16:17], v[16:17], 0, s[2:3]
	global_store_dword v[16:17], v18, off
.LBB0_1461:
	s_or_b64 exec, exec, s[28:29]
	v_add_u32_e32 v16, 0xb0, v142
	v_ashrrev_i32_e32 v17, 31, v16
	v_lshlrev_b64 v[18:19], 11, v[16:17]
	v_lshl_add_u64 v[18:19], s[10:11], 0, v[18:19]
	v_lshl_add_u64 v[18:19], v[140:141], 1, v[18:19]
	s_waitcnt vmcnt(31)
	v_lshlrev_b32_e32 v22, 16, v214
	v_and_b32_e32 v23, 0xffff0000, v214
	v_lshlrev_b32_e32 v20, 16, v215
	v_and_b32_e32 v21, 0xffff0000, v215
	v_pk_add_f32 v[14:15], v[14:15], v[20:21]
	v_pk_add_f32 v[12:13], v[12:13], v[22:23]
	s_nop 0
	v_cvt_pk_bf16_f32 v20, v12, v13
	v_cvt_pk_bf16_f32 v21, v14, v15
	v_mul_f32_e32 v13, v13, v13
	global_store_dwordx2 v[18:19], v[20:21], off
	v_mul_f32_e32 v15, v15, v15
	v_fmac_f32_e32 v13, v12, v12
	v_fmac_f32_e32 v15, v14, v14
	v_add_f32_e32 v12, v13, v15
	s_waitcnt vmcnt(31)
	v_lshlrev_b32_e32 v20, 16, v216
	v_and_b32_e32 v21, 0xffff0000, v216
	v_lshlrev_b32_e32 v22, 16, v217
	v_and_b32_e32 v23, 0xffff0000, v217
	v_pk_add_f32 v[10:11], v[10:11], v[22:23]
	v_pk_add_f32 v[8:9], v[8:9], v[20:21]
	s_nop 0
	v_cvt_pk_bf16_f32 v20, v8, v9
	v_cvt_pk_bf16_f32 v21, v10, v11
	v_mul_f32_e32 v9, v9, v9
	global_store_dwordx2 v[18:19], v[20:21], off offset:32
	v_mul_f32_e32 v11, v11, v11
	v_fmac_f32_e32 v9, v8, v8
	v_fmac_f32_e32 v11, v10, v10
	v_add_f32_e32 v8, v9, v11
	v_add_f32_e32 v8, v12, v8
	s_waitcnt vmcnt(31)
	v_lshlrev_b32_e32 v20, 16, v218
	v_and_b32_e32 v21, 0xffff0000, v218
	v_lshlrev_b32_e32 v22, 16, v219
	v_and_b32_e32 v23, 0xffff0000, v219
	v_pk_add_f32 v[6:7], v[6:7], v[22:23]
	v_pk_add_f32 v[4:5], v[4:5], v[20:21]
	s_nop 0
	v_cvt_pk_bf16_f32 v20, v4, v5
	v_cvt_pk_bf16_f32 v21, v6, v7
	v_mul_f32_e32 v5, v5, v5
	v_mul_f32_e32 v7, v7, v7
	v_fmac_f32_e32 v5, v4, v4
	v_fmac_f32_e32 v7, v6, v6
	v_add_f32_e32 v4, v5, v7
	v_add_f32_e32 v8, v8, v4
	global_store_dwordx2 v[18:19], v[20:21], off offset:256
	s_waitcnt vmcnt(31)
	v_lshlrev_b32_e32 v4, 16, v220
	v_and_b32_e32 v5, 0xffff0000, v220
	v_lshlrev_b32_e32 v6, 16, v221
	v_and_b32_e32 v7, 0xffff0000, v221
	v_pk_add_f32 v[2:3], v[2:3], v[6:7]
	v_pk_add_f32 v[0:1], v[0:1], v[4:5]
	v_mul_f32_e32 v5, v3, v3
	v_mul_f32_e32 v4, v1, v1
	v_fmac_f32_e32 v4, v0, v0
	v_fmac_f32_e32 v5, v2, v2
	v_add_f32_e32 v4, v4, v5
	v_add_f32_e32 v4, v8, v4
	ds_swizzle_b32 v5, v4 offset:swizzle(SWAP,16)
	v_cvt_pk_bf16_f32 v0, v0, v1
	v_cvt_pk_bf16_f32 v1, v2, v3
	global_store_dwordx2 v[18:19], v[0:1], off offset:288
	s_waitcnt lgkmcnt(0)
	v_add_f32_e32 v0, v4, v5
	v_mov_b32_e32 v1, v0
	s_nop 1
	v_permlane32_swap_b32_e32 v0, v1
	s_and_saveexec_b64 s[28:29], s[4:5]
	s_cbranch_execz .LBB0_1463
	v_add_f32_e32 v2, v0, v1
	v_lshlrev_b64 v[0:1], 6, v[16:17]
	v_lshl_add_u64 v[0:1], s[12:13], 0, v[0:1]
	v_lshl_add_u64 v[0:1], s[26:27], 2, v[0:1]
	s_lshl_b32 s2, s48, 2
	v_lshl_add_u64 v[0:1], v[0:1], 0, s[2:3]
	global_store_dword v[0:1], v2, off
